# nt policy on more full-line store streams: P7 XQ/BtUpQ, items X0/Hb, P9
# speedup vs baseline: 1.0036x; 1.0036x over previous
.LBB0_601:
	s_or_b64 exec, exec, s[10:11]
	s_waitcnt vmcnt(6)
	v_pk_mul_f32 v[230:231], v[14:15], v[130:131] op_sel_hi:[0,1]
	v_pk_fma_f32 v[230:231], v[10:11], v[116:117], v[230:231] op_sel_hi:[0,1,1]
	v_mov_b32_e32 v138, v117
	s_waitcnt vmcnt(5)
	v_pk_fma_f32 v[116:117], v[6:7], v[138:139], v[230:231] op_sel_hi:[0,1,1]
	v_pk_mul_f32 v[230:231], v[14:15], v[138:139] op_sel_hi:[0,1]
	v_pk_fma_f32 v[230:231], v[10:11], v[130:131], v[230:231] op_sel_hi:[0,1,1]
	v_mov_b32_e32 v152, v131
	v_pk_fma_f32 v[130:131], v[6:7], v[152:153], v[230:231] op_sel_hi:[0,1,1]
	v_pk_mul_f32 v[230:231], v[14:15], v[120:121] op_sel:[1,0]
	v_mov_b32_e32 v128, v105
	v_pk_fma_f32 v[230:231], v[10:11], v[104:105], v[230:231] op_sel:[1,0,0]
	v_mov_b32_e32 v142, v121
	v_pk_fma_f32 v[104:105], v[6:7], v[128:129], v[230:231] op_sel:[1,0,0]
	v_pk_mul_f32 v[230:231], v[14:15], v[128:129] op_sel:[1,0]
	v_mov_b32_e32 v178, v153
	v_pk_fma_f32 v[230:231], v[10:11], v[120:121], v[230:231] op_sel:[1,0,0]
	v_mov_b32_e32 v190, v169
	v_mov_b32_e32 v170, v143
	v_mov_b32_e32 v182, v159
	v_pk_fma_f32 v[120:121], v[6:7], v[142:143], v[230:231] op_sel:[1,0,0]
	v_pk_mul_f32 v[230:231], v[16:17], v[108:109] op_sel_hi:[0,1]
	v_mov_b32_e32 v168, v139
	v_pk_mul_f32 v[138:139], v[14:15], v[178:179] op_sel_hi:[0,1]
	v_pk_mul_f32 v[152:153], v[14:15], v[190:191] op_sel_hi:[0,1]
	v_mov_b32_e32 v158, v129
	v_pk_mul_f32 v[128:129], v[14:15], v[170:171] op_sel:[1,0]
	v_pk_mul_f32 v[14:15], v[14:15], v[182:183] op_sel:[1,0]
	v_pk_fma_f32 v[230:231], v[12:13], v[100:101], v[230:231] op_sel_hi:[0,1,1]
	v_mov_b32_e32 v118, v101
	v_pk_fma_f32 v[138:139], v[10:11], v[168:169], v[138:139] op_sel_hi:[0,1,1]
	v_pk_fma_f32 v[152:153], v[10:11], v[178:179], v[152:153] op_sel_hi:[0,1,1]
	v_mov_b32_e32 v198, v179
	v_pk_fma_f32 v[128:129], v[10:11], v[158:159], v[128:129] op_sel:[1,0,0]
	v_pk_fma_f32 v[10:11], v[10:11], v[170:171], v[14:15] op_sel:[1,0,0]
	v_mov_b32_e32 v192, v171
	v_pk_fma_f32 v[100:101], v[8:9], v[118:119], v[230:231] op_sel_hi:[0,1,1]
	v_pk_mul_f32 v[230:231], v[16:17], v[118:119] op_sel_hi:[0,1]
	v_pk_fma_f32 v[138:139], v[6:7], v[190:191], v[138:139] op_sel_hi:[0,1,1]
	v_pk_fma_f32 v[152:153], v[6:7], v[198:199], v[152:153] op_sel_hi:[0,1,1]
	v_pk_fma_f32 v[128:129], v[6:7], v[182:183], v[128:129] op_sel:[1,0,0]
	v_pk_fma_f32 v[6:7], v[6:7], v[192:193], v[10:11] op_sel:[1,0,0]
	v_mov_b32_e32 v164, v133
	v_mov_b32_e32 v174, v147
	s_waitcnt vmcnt(4)
	v_pk_add_f32 v[116:117], v[2:3], v[116:117] op_sel_hi:[0,1]
	v_pk_add_f32 v[130:131], v[2:3], v[130:131] op_sel_hi:[0,1]
	v_pk_add_f32 v[104:105], v[2:3], v[104:105] op_sel:[1,0]
	v_pk_add_f32 v[120:121], v[2:3], v[120:121] op_sel:[1,0]
	v_pk_fma_f32 v[230:231], v[12:13], v[108:109], v[230:231] op_sel_hi:[0,1,1]
	v_mov_b32_e32 v132, v109
	v_mov_b32_e32 v118, v17
	v_pk_add_f32 v[138:139], v[2:3], v[138:139] op_sel_hi:[0,1]
	v_pk_add_f32 v[152:153], v[2:3], v[152:153] op_sel_hi:[0,1]
	v_pk_add_f32 v[10:11], v[2:3], v[128:129] op_sel:[1,0]
	v_pk_add_f32 v[14:15], v[2:3], v[6:7] op_sel:[1,0]
	v_mov_b32_e32 v146, v119
	v_pk_mul_f32 v[2:3], v[16:17], v[164:165] op_sel_hi:[0,1]
	v_pk_mul_f32 v[6:7], v[16:17], v[174:175] op_sel_hi:[0,1]
	v_pk_fma_f32 v[108:109], v[8:9], v[132:133], v[230:231] op_sel_hi:[0,1,1]
	v_mov_b32_e32 v110, v13
	v_pk_mul_f32 v[230:231], v[118:119], v[98:99] op_sel_hi:[0,1]
	v_pk_fma_f32 v[2:3], v[12:13], v[146:147], v[2:3] op_sel_hi:[0,1,1]
	v_pk_fma_f32 v[6:7], v[12:13], v[164:165], v[6:7] op_sel_hi:[0,1,1]
	v_mov_b32_e32 v186, v165
	v_pk_fma_f32 v[230:231], v[110:111], v[96:97], v[230:231] op_sel_hi:[0,1,1]
	v_mov_b32_e32 v124, v9
	v_mov_b32_e32 v106, v97
	v_pk_fma_f32 v[2:3], v[8:9], v[174:175], v[2:3] op_sel_hi:[0,1,1]
	v_pk_fma_f32 v[6:7], v[8:9], v[186:187], v[6:7] op_sel_hi:[0,1,1]
	v_mov_b32_e32 v150, v123
	v_mov_b32_e32 v166, v135
	v_pk_add_f32 v[100:101], v[4:5], v[100:101] op_sel_hi:[0,1]
	v_pk_add_f32 v[108:109], v[4:5], v[108:109] op_sel_hi:[0,1]
	v_pk_fma_f32 v[96:97], v[124:125], v[106:107], v[230:231] op_sel_hi:[0,1,1]
	v_pk_mul_f32 v[230:231], v[118:119], v[106:107] op_sel_hi:[0,1]
	v_mov_b32_e32 v106, v5
	v_pk_add_f32 v[12:13], v[4:5], v[2:3] op_sel_hi:[0,1]
	v_pk_add_f32 v[16:17], v[4:5], v[6:7] op_sel_hi:[0,1]
	v_mov_b32_e32 v134, v107
	v_pk_mul_f32 v[2:3], v[118:119], v[150:151] op_sel_hi:[0,1]
	v_pk_mul_f32 v[4:5], v[118:119], v[166:167] op_sel_hi:[0,1]
	v_pk_fma_f32 v[230:231], v[110:111], v[98:99], v[230:231] op_sel_hi:[0,1,1]
	v_mov_b32_e32 v122, v99
	v_pk_fma_f32 v[2:3], v[110:111], v[134:135], v[2:3] op_sel_hi:[0,1,1]
	v_pk_fma_f32 v[4:5], v[110:111], v[150:151], v[4:5] op_sel_hi:[0,1,1]
	v_mov_b32_e32 v176, v151
	v_pk_fma_f32 v[230:231], v[124:125], v[122:123], v[230:231] op_sel_hi:[0,1,1]
	v_pk_fma_f32 v[2:3], v[124:125], v[166:167], v[2:3] op_sel_hi:[0,1,1]
	v_pk_fma_f32 v[4:5], v[124:125], v[176:177], v[4:5] op_sel_hi:[0,1,1]
	v_mov_b32_e32 v210, v185
	v_mov_b32_e32 v222, v219
	v_pk_add_f32 v[98:99], v[106:107], v[96:97] op_sel_hi:[0,1]
	v_pk_add_f32 v[96:97], v[106:107], v[230:231] op_sel_hi:[0,1]
	v_pk_add_f32 v[118:119], v[106:107], v[2:3] op_sel_hi:[0,1]
	v_pk_add_f32 v[4:5], v[106:107], v[4:5] op_sel_hi:[0,1]
	s_waitcnt vmcnt(2)
	v_pk_mul_f32 v[8:9], v[26:27], v[210:211] op_sel_hi:[0,1]
	v_mov_b32_e32 v220, v215
	v_pk_mul_f32 v[106:107], v[26:27], v[222:223] op_sel_hi:[0,1]
	v_lshl_add_u64 v[2:3], v[90:91], 1, s[8:9]
	v_pk_mul_f32 v[6:7], v[26:27], v[194:195] op_sel_hi:[0,1]
	v_pk_fma_f32 v[8:9], v[30:31], v[194:195], v[8:9] op_sel_hi:[0,1,1]
	v_mov_b32_e32 v214, v195
	v_mov_b32_e32 v218, v211
	v_pk_mul_f32 v[90:91], v[26:27], v[220:221] op_sel_hi:[0,1]
	v_pk_fma_f32 v[106:107], v[30:31], v[220:221], v[106:107] op_sel_hi:[0,1,1]
	v_mov_b32_e32 v224, v221
	v_pk_fma_f32 v[6:7], v[30:31], v[184:185], v[6:7] op_sel_hi:[0,1,1]
	s_waitcnt vmcnt(1)
	v_pk_fma_f32 v[8:9], v[22:23], v[214:215], v[8:9] op_sel_hi:[0,1,1]
	v_pk_fma_f32 v[90:91], v[30:31], v[218:219], v[90:91] op_sel_hi:[0,1,1]
	v_pk_fma_f32 v[106:107], v[22:23], v[224:225], v[106:107] op_sel_hi:[0,1,1]
	v_pk_fma_f32 v[6:7], v[22:23], v[210:211], v[6:7] op_sel_hi:[0,1,1]
	s_waitcnt vmcnt(0)
	v_pk_add_f32 v[8:9], v[18:19], v[8:9] op_sel_hi:[0,1]
	v_pk_fma_f32 v[90:91], v[22:23], v[222:223], v[90:91] op_sel_hi:[0,1,1]
	v_pk_add_f32 v[106:107], v[18:19], v[106:107] op_sel_hi:[0,1]
	v_pk_add_f32 v[6:7], v[18:19], v[6:7] op_sel_hi:[0,1]
	v_pk_mul_f32 v[8:9], v[130:131], v[8:9]
	v_pk_add_f32 v[90:91], v[18:19], v[90:91] op_sel_hi:[0,1]
	v_pk_mul_f32 v[106:107], v[152:153], v[106:107]
	v_pk_mul_f32 v[6:7], v[116:117], v[6:7]
	v_pk_mul_f32 v[90:91], v[138:139], v[90:91]
	v_bfe_u32 v110, v107, 16, 1
	v_bfe_u32 v116, v106, 16, 1
	v_bfe_u32 v117, v9, 16, 1
	v_bfe_u32 v122, v8, 16, 1
	v_add3_u32 v122, v8, v122, s67
	v_add3_u32 v117, v9, v117, s67
	v_add3_u32 v8, v106, v116, s67
	v_add3_u32 v9, v107, v110, s67
	v_bfe_u32 v110, v90, 16, 1
	v_bfe_u32 v116, v91, 16, 1
	v_add3_u32 v91, v91, v116, s67
	v_add3_u32 v90, v90, v110, s67
	v_bfe_u32 v106, v6, 16, 1
	v_bfe_u32 v107, v7, 16, 1
	v_lshrrev_b32_e32 v90, 16, v90
	v_lshrrev_b32_e32 v91, 16, v91
	s_mov_b32 s3, 0xffff0000
	v_add3_u32 v7, v7, v107, s67
	v_add3_u32 v6, v6, v106, s67
	v_and_or_b32 v9, v9, s3, v91
	v_and_or_b32 v8, v8, s3, v90
	v_lshl_add_u64 v[90:91], s[6:7], 0, v[54:55]
	v_lshrrev_b32_e32 v6, 16, v6
	v_lshrrev_b32_e32 v7, 16, v7
	v_lshlrev_b64 v[90:91], 12, v[90:91]
	v_and_or_b32 v7, v117, s3, v7
	v_and_or_b32 v6, v122, s3, v6
	v_lshl_add_u64 v[90:91], v[2:3], 0, v[90:91]
	v_mov_b32_e32 v196, v145
	v_mov_b32_e32 v208, v203
	v_mov_b32_e32 v212, v207
	global_store_dwordx4 v[90:91], v[6:9], off
	v_mov_b32_e32 v206, v197
	v_pk_mul_f32 v[90:91], v[26:27], v[208:209] op_sel:[1,0]
	v_pk_mul_f32 v[6:7], v[26:27], v[156:157] op_sel:[1,0]
	v_pk_mul_f32 v[8:9], v[26:27], v[196:197] op_sel:[1,0]
	v_pk_mul_f32 v[26:27], v[26:27], v[212:213] op_sel:[1,0]
	v_pk_fma_f32 v[6:7], v[30:31], v[144:145], v[6:7] op_sel:[1,0,0]
	v_pk_fma_f32 v[8:9], v[30:31], v[156:157], v[8:9] op_sel:[1,0,0]
	v_mov_b32_e32 v202, v157
	v_pk_fma_f32 v[90:91], v[30:31], v[206:207], v[90:91] op_sel:[1,0,0]
	v_pk_fma_f32 v[26:27], v[30:31], v[208:209], v[26:27] op_sel:[1,0,0]
	v_mov_b32_e32 v216, v209
	v_pk_fma_f32 v[6:7], v[22:23], v[196:197], v[6:7] op_sel:[1,0,0]
	v_pk_fma_f32 v[8:9], v[22:23], v[202:203], v[8:9] op_sel:[1,0,0]
	v_pk_fma_f32 v[90:91], v[22:23], v[212:213], v[90:91] op_sel:[1,0,0]
	v_pk_fma_f32 v[22:23], v[22:23], v[216:217], v[26:27] op_sel:[1,0,0]
	v_pk_add_f32 v[6:7], v[18:19], v[6:7] op_sel:[1,0]
	v_pk_add_f32 v[8:9], v[18:19], v[8:9] op_sel:[1,0]
	v_pk_add_f32 v[90:91], v[18:19], v[90:91] op_sel:[1,0]
	v_pk_add_f32 v[18:19], v[18:19], v[22:23] op_sel:[1,0]
	v_pk_mul_f32 v[8:9], v[120:121], v[8:9]
	v_pk_mul_f32 v[14:15], v[14:15], v[18:19]
	v_pk_mul_f32 v[10:11], v[10:11], v[90:91]
	v_bfe_u32 v18, v15, 16, 1
	v_bfe_u32 v19, v14, 16, 1
	v_bfe_u32 v22, v9, 16, 1
	v_bfe_u32 v23, v8, 16, 1
	v_add3_u32 v23, v8, v23, s67
	v_add3_u32 v22, v9, v22, s67
	v_add3_u32 v8, v14, v19, s67
	v_add3_u32 v9, v15, v18, s67
	v_bfe_u32 v18, v10, 16, 1
	v_bfe_u32 v19, v11, 16, 1
	v_pk_mul_f32 v[6:7], v[104:105], v[6:7]
	v_add3_u32 v11, v11, v19, s67
	v_add3_u32 v10, v10, v18, s67
	v_bfe_u32 v14, v6, 16, 1
	v_bfe_u32 v15, v7, 16, 1
	v_lshrrev_b32_e32 v10, 16, v10
	v_lshrrev_b32_e32 v11, 16, v11
	v_add3_u32 v7, v7, v15, s67
	v_add3_u32 v6, v6, v14, s67
	v_and_or_b32 v9, v9, s3, v11
	v_and_or_b32 v8, v8, s3, v10
	v_lshl_add_u64 v[10:11], s[6:7], 0, v[56:57]
	v_lshrrev_b32_e32 v6, 16, v6
	v_lshrrev_b32_e32 v7, 16, v7
	v_lshlrev_b64 v[10:11], 12, v[10:11]
	v_and_or_b32 v7, v22, s3, v7
	v_and_or_b32 v6, v23, s3, v6
	v_lshl_add_u64 v[10:11], v[2:3], 0, v[10:11]
	v_mov_b32_e32 v188, v173
	global_store_dwordx4 v[10:11], v[6:9], off
	v_mov_b32_e32 v180, v155
	v_pk_mul_f32 v[10:11], v[28:29], v[188:189] op_sel_hi:[0,1]
	v_pk_fma_f32 v[10:11], v[32:33], v[180:181], v[10:11] op_sel_hi:[0,1,1]
	v_mov_b32_e32 v200, v181
	v_pk_fma_f32 v[10:11], v[24:25], v[200:201], v[10:11] op_sel_hi:[0,1,1]
	v_mov_b32_e32 v154, v103
	v_pk_add_f32 v[10:11], v[20:21], v[10:11] op_sel_hi:[0,1]
	v_pk_mul_f32 v[8:9], v[28:29], v[154:155] op_sel_hi:[0,1]
	v_pk_mul_f32 v[10:11], v[12:13], v[10:11]
	v_pk_mul_f32 v[12:13], v[28:29], v[200:201] op_sel_hi:[0,1]
	v_pk_fma_f32 v[8:9], v[32:33], v[112:113], v[8:9] op_sel_hi:[0,1,1]
	v_mov_b32_e32 v172, v113
	v_pk_fma_f32 v[12:13], v[32:33], v[188:189], v[12:13] op_sel_hi:[0,1,1]
	v_mov_b32_e32 v204, v189
	v_pk_fma_f32 v[8:9], v[24:25], v[172:173], v[8:9] op_sel_hi:[0,1,1]
	v_pk_fma_f32 v[12:13], v[24:25], v[204:205], v[12:13] op_sel_hi:[0,1,1]
	v_pk_mul_f32 v[6:7], v[28:29], v[112:113] op_sel_hi:[0,1]
	v_pk_add_f32 v[8:9], v[20:21], v[8:9] op_sel_hi:[0,1]
	v_pk_add_f32 v[12:13], v[20:21], v[12:13] op_sel_hi:[0,1]
	v_pk_fma_f32 v[6:7], v[32:33], v[102:103], v[6:7] op_sel_hi:[0,1,1]
	v_pk_mul_f32 v[8:9], v[108:109], v[8:9]
	v_pk_mul_f32 v[12:13], v[16:17], v[12:13]
	v_pk_fma_f32 v[6:7], v[24:25], v[154:155], v[6:7] op_sel_hi:[0,1,1]
	v_bfe_u32 v14, v13, 16, 1
	v_bfe_u32 v15, v12, 16, 1
	v_bfe_u32 v16, v9, 16, 1
	v_bfe_u32 v17, v8, 16, 1
	v_pk_add_f32 v[6:7], v[20:21], v[6:7] op_sel_hi:[0,1]
	v_add3_u32 v17, v8, v17, s67
	v_add3_u32 v16, v9, v16, s67
	v_add3_u32 v8, v12, v15, s67
	v_add3_u32 v9, v13, v14, s67
	v_bfe_u32 v14, v10, 16, 1
	v_bfe_u32 v15, v11, 16, 1
	v_pk_mul_f32 v[6:7], v[100:101], v[6:7]
	v_add3_u32 v11, v11, v15, s67
	v_add3_u32 v10, v10, v14, s67
	v_bfe_u32 v12, v6, 16, 1
	v_bfe_u32 v13, v7, 16, 1
	v_lshrrev_b32_e32 v10, 16, v10
	v_lshrrev_b32_e32 v11, 16, v11
	v_add3_u32 v7, v7, v13, s67
	v_add3_u32 v6, v6, v12, s67
	v_and_or_b32 v9, v9, s3, v11
	v_and_or_b32 v8, v8, s3, v10
	v_lshl_add_u64 v[10:11], s[6:7], 0, v[58:59]
	v_lshrrev_b32_e32 v6, 16, v6
	v_lshrrev_b32_e32 v7, 16, v7
	v_lshlrev_b64 v[10:11], 12, v[10:11]
	v_and_or_b32 v7, v16, s3, v7
	v_and_or_b32 v6, v17, s3, v6
	v_lshl_add_u64 v[10:11], v[2:3], 0, v[10:11]
	global_store_dwordx4 v[10:11], v[6:9], off
	v_mov_b32_e32 v110, v93
	v_mov_b32_e32 v148, v125
	v_mov_b32_e32 v8, v29
	v_mov_b32_e32 v140, v137
	v_mov_b32_e32 v6, v33
	v_pk_mul_f32 v[10:11], v[8:9], v[94:95] op_sel_hi:[0,1]
	v_pk_mul_f32 v[16:17], v[8:9], v[110:111] op_sel_hi:[0,1]
	v_mov_b32_e32 v136, v111
	v_pk_mul_f32 v[18:19], v[8:9], v[148:149] op_sel_hi:[0,1]
	v_pk_mul_f32 v[8:9], v[8:9], v[140:141] op_sel_hi:[0,1]
	v_pk_fma_f32 v[10:11], v[6:7], v[92:93], v[10:11] op_sel_hi:[0,1,1]
	v_mov_b32_e32 v12, v25
	v_pk_fma_f32 v[16:17], v[6:7], v[94:95], v[16:17] op_sel_hi:[0,1,1]
	v_pk_fma_f32 v[18:19], v[6:7], v[136:137], v[18:19] op_sel_hi:[0,1,1]
	v_pk_fma_f32 v[6:7], v[6:7], v[148:149], v[8:9] op_sel_hi:[0,1,1]
	v_mov_b32_e32 v126, v149
	v_mov_b32_e32 v14, v21
	v_pk_fma_f32 v[6:7], v[12:13], v[126:127], v[6:7] op_sel_hi:[0,1,1]
	v_pk_fma_f32 v[10:11], v[12:13], v[110:111], v[10:11] op_sel_hi:[0,1,1]
	v_mov_b32_e32 v124, v95
	v_pk_fma_f32 v[18:19], v[12:13], v[140:141], v[18:19] op_sel_hi:[0,1,1]
	v_pk_add_f32 v[6:7], v[14:15], v[6:7] op_sel_hi:[0,1]
	v_pk_add_f32 v[10:11], v[14:15], v[10:11] op_sel_hi:[0,1]
	v_pk_fma_f32 v[16:17], v[12:13], v[124:125], v[16:17] op_sel_hi:[0,1,1]
	v_pk_add_f32 v[18:19], v[14:15], v[18:19] op_sel_hi:[0,1]
	v_pk_mul_f32 v[4:5], v[4:5], v[6:7]
	v_pk_mul_f32 v[10:11], v[98:99], v[10:11]
	v_pk_add_f32 v[16:17], v[14:15], v[16:17] op_sel_hi:[0,1]
	v_pk_mul_f32 v[18:19], v[118:119], v[18:19]
	v_bfe_u32 v6, v5, 16, 1
	v_bfe_u32 v7, v4, 16, 1
	v_pk_mul_f32 v[16:17], v[96:97], v[16:17]
	v_add3_u32 v4, v4, v7, s67
	v_add3_u32 v5, v5, v6, s67
	v_bfe_u32 v6, v10, 16, 1
	v_bfe_u32 v7, v11, 16, 1
	v_bfe_u32 v12, v18, 16, 1
	v_bfe_u32 v13, v19, 16, 1
	v_bfe_u32 v8, v17, 16, 1
	v_bfe_u32 v9, v16, 16, 1
	v_add3_u32 v13, v19, v13, s67
	v_add3_u32 v12, v18, v12, s67
	v_add3_u32 v7, v11, v7, s67
	v_add3_u32 v6, v10, v6, s67
	v_add3_u32 v9, v16, v9, s67
	v_add3_u32 v8, v17, v8, s67
	v_lshrrev_b32_e32 v10, 16, v6
	v_lshrrev_b32_e32 v11, 16, v7
	v_lshrrev_b32_e32 v6, 16, v12
	v_lshrrev_b32_e32 v7, 16, v13
	v_and_or_b32 v7, v5, s3, v7
	v_and_or_b32 v6, v4, s3, v6
	v_and_or_b32 v5, v8, s3, v11
	v_and_or_b32 v4, v9, s3, v10
	v_lshl_add_u64 v[8:9], s[6:7], 0, v[60:61]
	v_lshlrev_b64 v[8:9], 12, v[8:9]
	v_lshl_add_u64 v[2:3], v[2:3], 0, v[8:9]
	global_store_dwordx4 v[2:3], v[4:7], off
	global_load_dwordx4 v[2:5], v[38:39], off
	s_nop 0
	global_load_dwordx4 v[14:17], v[62:63], off
	global_load_dwordx4 v[6:9], v[64:65], off
	global_load_dwordx4 v[10:13], v[44:45], off
	v_and_b32_e32 v28, 0xffff0000, v85
	v_and_b32_e32 v30, 0xffff0000, v84
	v_cndmask_b32_e64 v29, 0, v28, s[44:45]
	v_cndmask_b32_e64 v28, 0, v30, s[44:45]
	v_lshlrev_b32_e32 v30, 16, v82
	v_and_b32_e32 v32, 0xffff0000, v83
	v_and_b32_e32 v82, 0xffff0000, v82
	v_lshlrev_b32_e32 v26, 16, v84
	v_lshlrev_b32_e32 v27, 16, v85
	v_lshlrev_b32_e32 v31, 16, v83
	v_cndmask_b32_e64 v33, 0, v32, s[44:45]
	v_cndmask_b32_e64 v32, 0, v82, s[44:45]
	v_lshlrev_b32_e32 v82, 16, v80
	v_lshlrev_b32_e32 v83, 16, v81
	v_and_b32_e32 v84, 0xffff0000, v81
	v_and_b32_e32 v85, 0xffff0000, v80
	v_lshlrev_b32_e32 v22, 16, v86
	v_and_b32_e32 v24, 0xffff0000, v86
	v_lshlrev_b32_e32 v23, 16, v87
	v_and_b32_e32 v25, 0xffff0000, v87
	v_cndmask_b32_e64 v81, 0, v83, s[44:45]
	v_cndmask_b32_e64 v80, 0, v82, s[44:45]
	v_cndmask_b32_e64 v83, 0, v84, s[44:45]
	v_cndmask_b32_e64 v82, 0, v85, s[44:45]
	v_lshlrev_b32_e32 v84, 16, v78
	v_lshlrev_b32_e32 v85, 16, v79
	v_and_b32_e32 v86, 0xffff0000, v79
	v_and_b32_e32 v87, 0xffff0000, v78
	v_lshlrev_b32_e32 v18, 16, v88
	v_and_b32_e32 v20, 0xffff0000, v88
	v_lshlrev_b32_e32 v19, 16, v89
	v_and_b32_e32 v21, 0xffff0000, v89
	v_cndmask_b32_e64 v79, 0, v85, s[44:45]
	v_cndmask_b32_e64 v78, 0, v84, s[44:45]
	v_cndmask_b32_e64 v85, 0, v86, s[44:45]
	v_cndmask_b32_e64 v84, 0, v87, s[44:45]
	v_lshlrev_b32_e32 v86, 16, v76
	v_lshlrev_b32_e32 v87, 16, v77
	v_and_b32_e32 v88, 0xffff0000, v77
	v_and_b32_e32 v89, 0xffff0000, v76
	v_cndmask_b32_e64 v77, 0, v87, s[44:45]
	v_cndmask_b32_e64 v76, 0, v86, s[44:45]
	v_cndmask_b32_e64 v87, 0, v88, s[44:45]
	v_cndmask_b32_e64 v86, 0, v89, s[44:45]
	v_lshlrev_b32_e32 v88, 16, v74
	v_lshlrev_b32_e32 v89, 16, v75
	v_and_b32_e32 v90, 0xffff0000, v75
	v_and_b32_e32 v91, 0xffff0000, v74
	v_cndmask_b32_e64 v75, 0, v89, s[44:45]
	v_cndmask_b32_e64 v74, 0, v88, s[44:45]
	v_cndmask_b32_e64 v89, 0, v90, s[44:45]
	v_cndmask_b32_e64 v88, 0, v91, s[44:45]
	v_lshlrev_b32_e32 v90, 16, v72
	v_lshlrev_b32_e32 v91, 16, v73
	v_and_b32_e32 v92, 0xffff0000, v73
	v_and_b32_e32 v93, 0xffff0000, v72
	v_cndmask_b32_e64 v23, 0, v23, s[44:45]
	v_cndmask_b32_e64 v22, 0, v22, s[44:45]
	v_cndmask_b32_e64 v25, 0, v25, s[44:45]
	v_cndmask_b32_e64 v24, 0, v24, s[44:45]
	v_cndmask_b32_e64 v73, 0, v91, s[44:45]
	v_cndmask_b32_e64 v72, 0, v90, s[44:45]
	v_cndmask_b32_e64 v91, 0, v92, s[44:45]
	v_cndmask_b32_e64 v90, 0, v93, s[44:45]
	v_lshlrev_b32_e32 v92, 16, v70
	v_lshlrev_b32_e32 v93, 16, v71
	v_and_b32_e32 v94, 0xffff0000, v71
	v_and_b32_e32 v95, 0xffff0000, v70
	v_cndmask_b32_e64 v19, 0, v19, s[46:47]
	v_cndmask_b32_e64 v18, 0, v18, s[46:47]
	v_cndmask_b32_e64 v21, 0, v21, s[46:47]
	v_cndmask_b32_e64 v20, 0, v20, s[46:47]
	v_cndmask_b32_e64 v71, 0, v93, s[48:49]
	v_cndmask_b32_e64 v70, 0, v92, s[48:49]
	v_cndmask_b32_e64 v93, 0, v94, s[48:49]
	v_cndmask_b32_e64 v92, 0, v95, s[48:49]
	s_waitcnt vmcnt(3)
	v_mov_b32_e32 v94, v2
	s_waitcnt vmcnt(2)
	v_mov_b32_e32 v96, v14
	v_mov_b32_e32 v97, v16
	v_mov_b32_e32 v16, v15
	v_mov_b32_e32 v95, v4
	v_pk_mul_f32 v[98:99], v[96:97], v[22:23]
	v_mov_b32_e32 v4, v3
	v_pk_mul_f32 v[2:3], v[16:17], v[24:25]
	v_pk_fma_f32 v[18:19], v[94:95], v[18:19], v[98:99]
	s_waitcnt vmcnt(1)
	v_mov_b32_e32 v99, v8
	v_pk_fma_f32 v[2:3], v[4:5], v[20:21], v[2:3]
	v_mov_b32_e32 v8, v7
	v_cndmask_b32_e64 v27, 0, v27, s[44:45]
	v_cndmask_b32_e64 v26, 0, v26, s[44:45]
	v_mov_b32_e32 v98, v6
	s_waitcnt vmcnt(0)
	v_mov_b32_e32 v101, v12
	v_pk_fma_f32 v[2:3], v[8:9], v[28:29], v[2:3]
	v_mov_b32_e32 v12, v11
	v_pk_fma_f32 v[18:19], v[98:99], v[26:27], v[18:19]
	v_mov_b32_e32 v100, v10
	v_pk_add_f32 v[2:3], v[12:13], v[2:3]
	v_pk_add_f32 v[18:19], v[100:101], v[18:19]
	v_and_b32_sdwa v10, v3, v228 dst_sel:DWORD dst_unused:UNUSED_PAD src0_sel:WORD_1 src1_sel:DWORD
	v_and_b32_sdwa v11, v2, v228 dst_sel:DWORD dst_unused:UNUSED_PAD src0_sel:WORD_1 src1_sel:DWORD
	v_and_b32_sdwa v6, v19, v228 dst_sel:DWORD dst_unused:UNUSED_PAD src0_sel:WORD_1 src1_sel:DWORD
	v_and_b32_sdwa v7, v18, v228 dst_sel:DWORD dst_unused:UNUSED_PAD src0_sel:WORD_1 src1_sel:DWORD
	v_add3_u32 v3, v3, v10, s67
	v_add3_u32 v2, v2, v11, s67
	v_add3_u32 v7, v18, v7, s67
	v_add3_u32 v6, v19, v6, s67
	v_and_b32_e32 v3, 0xffff0000, v3
	v_and_b32_e32 v2, 0xffff0000, v2
	v_or_b32_sdwa v3, v6, v3 dst_sel:DWORD dst_unused:UNUSED_PAD src0_sel:WORD_1 src1_sel:DWORD
	v_or_b32_sdwa v2, v7, v2 dst_sel:DWORD dst_unused:UNUSED_PAD src0_sel:WORD_1 src1_sel:DWORD
	v_lshlrev_b64 v[6:7], 10, v[68:69]
	v_lshl_add_u64 v[6:7], v[66:67], 0, v[6:7]
	global_store_dwordx2 v[6:7], v[2:3], off nt
	v_pk_mul_f32 v[2:3], v[96:97], v[26:27]
	v_cndmask_b32_e64 v31, 0, v31, s[44:45]
	v_cndmask_b32_e64 v30, 0, v30, s[44:45]
	v_pk_fma_f32 v[2:3], v[94:95], v[22:23], v[2:3]
	v_pk_mul_f32 v[10:11], v[16:17], v[28:29]
	v_pk_fma_f32 v[2:3], v[98:99], v[30:31], v[2:3]
	v_pk_fma_f32 v[10:11], v[4:5], v[24:25], v[10:11]
	v_pk_add_f32 v[2:3], v[100:101], v[2:3]
	v_pk_fma_f32 v[10:11], v[8:9], v[32:33], v[10:11]
	v_and_b32_sdwa v14, v3, v228 dst_sel:DWORD dst_unused:UNUSED_PAD src0_sel:WORD_1 src1_sel:DWORD
	v_pk_add_f32 v[10:11], v[12:13], v[10:11]
	v_and_b32_sdwa v15, v2, v228 dst_sel:DWORD dst_unused:UNUSED_PAD src0_sel:WORD_1 src1_sel:DWORD
	v_add3_u32 v2, v2, v15, s67
	v_add3_u32 v3, v3, v14, s67
	v_and_b32_sdwa v14, v11, v228 dst_sel:DWORD dst_unused:UNUSED_PAD src0_sel:WORD_1 src1_sel:DWORD
	v_and_b32_sdwa v15, v10, v228 dst_sel:DWORD dst_unused:UNUSED_PAD src0_sel:WORD_1 src1_sel:DWORD
	v_add3_u32 v11, v11, v14, s67
	v_add3_u32 v10, v10, v15, s67
	v_and_b32_e32 v11, 0xffff0000, v11
	v_and_b32_e32 v10, 0xffff0000, v10
	v_or_b32_sdwa v3, v3, v11 dst_sel:DWORD dst_unused:UNUSED_PAD src0_sel:WORD_1 src1_sel:DWORD
	v_or_b32_sdwa v2, v2, v10 dst_sel:DWORD dst_unused:UNUSED_PAD src0_sel:WORD_1 src1_sel:DWORD
	global_store_dwordx2 v[6:7], v[2:3], off offset:1024 nt
	v_pk_mul_f32 v[2:3], v[96:97], v[30:31]
	v_pk_mul_f32 v[10:11], v[16:17], v[32:33]
	v_pk_fma_f32 v[2:3], v[94:95], v[26:27], v[2:3]
	v_pk_fma_f32 v[10:11], v[4:5], v[28:29], v[10:11]
	v_pk_fma_f32 v[2:3], v[98:99], v[80:81], v[2:3]
	v_pk_fma_f32 v[10:11], v[8:9], v[82:83], v[10:11]
	v_pk_add_f32 v[2:3], v[100:101], v[2:3]
	v_pk_add_f32 v[10:11], v[12:13], v[10:11]
	v_and_b32_sdwa v14, v3, v228 dst_sel:DWORD dst_unused:UNUSED_PAD src0_sel:WORD_1 src1_sel:DWORD
	v_and_b32_sdwa v15, v2, v228 dst_sel:DWORD dst_unused:UNUSED_PAD src0_sel:WORD_1 src1_sel:DWORD
	v_add3_u32 v2, v2, v15, s67
	v_add3_u32 v3, v3, v14, s67
	v_and_b32_sdwa v14, v11, v228 dst_sel:DWORD dst_unused:UNUSED_PAD src0_sel:WORD_1 src1_sel:DWORD
	v_and_b32_sdwa v15, v10, v228 dst_sel:DWORD dst_unused:UNUSED_PAD src0_sel:WORD_1 src1_sel:DWORD
	v_add3_u32 v11, v11, v14, s67
	v_add3_u32 v10, v10, v15, s67
	v_and_b32_e32 v11, 0xffff0000, v11
	v_and_b32_e32 v10, 0xffff0000, v10
	v_or_b32_sdwa v3, v3, v11 dst_sel:DWORD dst_unused:UNUSED_PAD src0_sel:WORD_1 src1_sel:DWORD
	v_or_b32_sdwa v2, v2, v10 dst_sel:DWORD dst_unused:UNUSED_PAD src0_sel:WORD_1 src1_sel:DWORD
	global_store_dwordx2 v[6:7], v[2:3], off offset:2048 nt
	v_pk_mul_f32 v[2:3], v[96:97], v[80:81]
	v_pk_mul_f32 v[10:11], v[16:17], v[82:83]
	v_pk_fma_f32 v[2:3], v[94:95], v[30:31], v[2:3]
	v_pk_fma_f32 v[10:11], v[4:5], v[32:33], v[10:11]
	v_pk_fma_f32 v[2:3], v[98:99], v[78:79], v[2:3]
	v_pk_fma_f32 v[10:11], v[8:9], v[84:85], v[10:11]
	v_pk_add_f32 v[2:3], v[100:101], v[2:3]
	v_pk_add_f32 v[10:11], v[12:13], v[10:11]
	v_and_b32_sdwa v14, v3, v228 dst_sel:DWORD dst_unused:UNUSED_PAD src0_sel:WORD_1 src1_sel:DWORD
	v_and_b32_sdwa v15, v2, v228 dst_sel:DWORD dst_unused:UNUSED_PAD src0_sel:WORD_1 src1_sel:DWORD
	v_add3_u32 v2, v2, v15, s67
	v_add3_u32 v3, v3, v14, s67
	v_and_b32_sdwa v14, v11, v228 dst_sel:DWORD dst_unused:UNUSED_PAD src0_sel:WORD_1 src1_sel:DWORD
	v_and_b32_sdwa v15, v10, v228 dst_sel:DWORD dst_unused:UNUSED_PAD src0_sel:WORD_1 src1_sel:DWORD
	v_add3_u32 v11, v11, v14, s67
	v_add3_u32 v10, v10, v15, s67
	v_and_b32_e32 v11, 0xffff0000, v11
	v_and_b32_e32 v10, 0xffff0000, v10
	v_or_b32_sdwa v3, v3, v11 dst_sel:DWORD dst_unused:UNUSED_PAD src0_sel:WORD_1 src1_sel:DWORD
	v_or_b32_sdwa v2, v2, v10 dst_sel:DWORD dst_unused:UNUSED_PAD src0_sel:WORD_1 src1_sel:DWORD
	global_store_dwordx2 v[6:7], v[2:3], off offset:3072 nt
	v_pk_mul_f32 v[2:3], v[96:97], v[78:79]
	v_pk_mul_f32 v[10:11], v[16:17], v[84:85]
	v_pk_fma_f32 v[2:3], v[94:95], v[80:81], v[2:3]
	v_pk_fma_f32 v[10:11], v[4:5], v[82:83], v[10:11]
	v_pk_fma_f32 v[2:3], v[98:99], v[76:77], v[2:3]
	v_pk_fma_f32 v[10:11], v[8:9], v[86:87], v[10:11]
	v_pk_add_f32 v[2:3], v[100:101], v[2:3]
	v_pk_add_f32 v[10:11], v[12:13], v[10:11]
	v_and_b32_sdwa v14, v3, v228 dst_sel:DWORD dst_unused:UNUSED_PAD src0_sel:WORD_1 src1_sel:DWORD
	v_and_b32_sdwa v15, v2, v228 dst_sel:DWORD dst_unused:UNUSED_PAD src0_sel:WORD_1 src1_sel:DWORD
	v_add3_u32 v2, v2, v15, s67
	v_add3_u32 v3, v3, v14, s67
	v_and_b32_sdwa v14, v11, v228 dst_sel:DWORD dst_unused:UNUSED_PAD src0_sel:WORD_1 src1_sel:DWORD
	v_and_b32_sdwa v15, v10, v228 dst_sel:DWORD dst_unused:UNUSED_PAD src0_sel:WORD_1 src1_sel:DWORD
	v_add3_u32 v11, v11, v14, s67
	v_add3_u32 v10, v10, v15, s67
	v_and_b32_e32 v11, 0xffff0000, v11
	v_and_b32_e32 v10, 0xffff0000, v10
	v_add_co_u32_e32 v6, vcc, s63, v6
	v_or_b32_sdwa v3, v3, v11 dst_sel:DWORD dst_unused:UNUSED_PAD src0_sel:WORD_1 src1_sel:DWORD
	v_or_b32_sdwa v2, v2, v10 dst_sel:DWORD dst_unused:UNUSED_PAD src0_sel:WORD_1 src1_sel:DWORD
	v_addc_co_u32_e32 v7, vcc, 0, v7, vcc
	global_store_dwordx2 v[6:7], v[2:3], off nt
	v_pk_mul_f32 v[2:3], v[96:97], v[76:77]
	v_pk_mul_f32 v[10:11], v[16:17], v[86:87]
	v_pk_fma_f32 v[2:3], v[94:95], v[78:79], v[2:3]
	v_pk_fma_f32 v[10:11], v[4:5], v[84:85], v[10:11]
	v_pk_fma_f32 v[2:3], v[98:99], v[74:75], v[2:3]
	v_pk_fma_f32 v[10:11], v[8:9], v[88:89], v[10:11]
	v_pk_add_f32 v[2:3], v[100:101], v[2:3]
	v_pk_add_f32 v[10:11], v[12:13], v[10:11]
	v_and_b32_sdwa v14, v3, v228 dst_sel:DWORD dst_unused:UNUSED_PAD src0_sel:WORD_1 src1_sel:DWORD
	v_and_b32_sdwa v15, v2, v228 dst_sel:DWORD dst_unused:UNUSED_PAD src0_sel:WORD_1 src1_sel:DWORD
	v_add3_u32 v2, v2, v15, s67
	v_add3_u32 v3, v3, v14, s67
	v_and_b32_sdwa v14, v11, v228 dst_sel:DWORD dst_unused:UNUSED_PAD src0_sel:WORD_1 src1_sel:DWORD
	v_and_b32_sdwa v15, v10, v228 dst_sel:DWORD dst_unused:UNUSED_PAD src0_sel:WORD_1 src1_sel:DWORD
	v_add3_u32 v11, v11, v14, s67
	v_add3_u32 v10, v10, v15, s67
	v_and_b32_e32 v11, 0xffff0000, v11
	v_and_b32_e32 v10, 0xffff0000, v10
	v_or_b32_sdwa v3, v3, v11 dst_sel:DWORD dst_unused:UNUSED_PAD src0_sel:WORD_1 src1_sel:DWORD
	v_or_b32_sdwa v2, v2, v10 dst_sel:DWORD dst_unused:UNUSED_PAD src0_sel:WORD_1 src1_sel:DWORD
	global_store_dwordx2 v[6:7], v[2:3], off offset:1024 nt
	v_pk_mul_f32 v[2:3], v[96:97], v[74:75]
	v_pk_mul_f32 v[10:11], v[16:17], v[88:89]
	v_pk_fma_f32 v[2:3], v[94:95], v[76:77], v[2:3]
	v_pk_fma_f32 v[10:11], v[4:5], v[86:87], v[10:11]
	v_pk_fma_f32 v[2:3], v[98:99], v[72:73], v[2:3]
	v_pk_fma_f32 v[10:11], v[8:9], v[90:91], v[10:11]
	v_pk_add_f32 v[2:3], v[100:101], v[2:3]
	v_pk_add_f32 v[10:11], v[12:13], v[10:11]
	v_and_b32_sdwa v14, v3, v228 dst_sel:DWORD dst_unused:UNUSED_PAD src0_sel:WORD_1 src1_sel:DWORD
	v_and_b32_sdwa v15, v2, v228 dst_sel:DWORD dst_unused:UNUSED_PAD src0_sel:WORD_1 src1_sel:DWORD
	v_add3_u32 v2, v2, v15, s67
	v_add3_u32 v3, v3, v14, s67
	v_and_b32_sdwa v14, v11, v228 dst_sel:DWORD dst_unused:UNUSED_PAD src0_sel:WORD_1 src1_sel:DWORD
	v_and_b32_sdwa v15, v10, v228 dst_sel:DWORD dst_unused:UNUSED_PAD src0_sel:WORD_1 src1_sel:DWORD
	v_add3_u32 v11, v11, v14, s67
	v_add3_u32 v10, v10, v15, s67
	v_and_b32_e32 v11, 0xffff0000, v11
	v_and_b32_e32 v10, 0xffff0000, v10
	v_or_b32_sdwa v3, v3, v11 dst_sel:DWORD dst_unused:UNUSED_PAD src0_sel:WORD_1 src1_sel:DWORD
	v_or_b32_sdwa v2, v2, v10 dst_sel:DWORD dst_unused:UNUSED_PAD src0_sel:WORD_1 src1_sel:DWORD
	global_store_dwordx2 v[6:7], v[2:3], off offset:2048 nt
	v_pk_mul_f32 v[2:3], v[96:97], v[72:73]
	v_pk_mul_f32 v[10:11], v[16:17], v[90:91]
	v_pk_fma_f32 v[2:3], v[94:95], v[74:75], v[2:3]
	v_pk_fma_f32 v[4:5], v[4:5], v[88:89], v[10:11]
	v_pk_fma_f32 v[2:3], v[98:99], v[70:71], v[2:3]
	v_pk_fma_f32 v[4:5], v[8:9], v[92:93], v[4:5]
	v_pk_add_f32 v[2:3], v[100:101], v[2:3]
	v_pk_add_f32 v[4:5], v[12:13], v[4:5]
	v_and_b32_sdwa v8, v3, v228 dst_sel:DWORD dst_unused:UNUSED_PAD src0_sel:WORD_1 src1_sel:DWORD
	v_and_b32_sdwa v9, v2, v228 dst_sel:DWORD dst_unused:UNUSED_PAD src0_sel:WORD_1 src1_sel:DWORD
	v_add3_u32 v2, v2, v9, s67
	v_add3_u32 v3, v3, v8, s67
	v_and_b32_sdwa v8, v5, v228 dst_sel:DWORD dst_unused:UNUSED_PAD src0_sel:WORD_1 src1_sel:DWORD
	v_and_b32_sdwa v9, v4, v228 dst_sel:DWORD dst_unused:UNUSED_PAD src0_sel:WORD_1 src1_sel:DWORD
	v_add3_u32 v5, v5, v8, s67
	v_add3_u32 v4, v4, v9, s67
	v_and_b32_e32 v5, 0xffff0000, v5
	v_and_b32_e32 v4, 0xffff0000, v4
	v_or_b32_sdwa v3, v3, v5 dst_sel:DWORD dst_unused:UNUSED_PAD src0_sel:WORD_1 src1_sel:DWORD
	v_or_b32_sdwa v2, v2, v4 dst_sel:DWORD dst_unused:UNUSED_PAD src0_sel:WORD_1 src1_sel:DWORD
	global_store_dwordx2 v[6:7], v[2:3], off offset:3072 nt

.LBB0_607:
	s_or_b64 exec, exec, s[6:7]
	v_mov_b32_e32 v10, s13
	s_waitcnt lgkmcnt(0)
	s_barrier
	ds_read_b128 v[82:85], v10
	ds_read_b128 v[10:13], v10 offset:16
	s_waitcnt lgkmcnt(1)
	v_add_f32_e32 v6, v6, v82
	v_fmamk_f32 v6, v6, 0x3b000000, v1
	v_mul_f32_e32 v82, 0x4f800000, v6
	v_cmp_gt_f32_e32 vcc, s70, v6
	v_add_f32_e32 v8, v8, v84
	v_fmamk_f32 v8, v8, 0x3b000000, v1
	v_cndmask_b32_e32 v6, v6, v82, vcc
	v_sqrt_f32_e32 v82, v6
	s_waitcnt lgkmcnt(0)
	v_add_f32_e32 v2, v2, v10
	v_fmamk_f32 v2, v2, 0x3b000000, v1
	v_mul_f32_e32 v10, 0x4f800000, v2
	v_add_u32_e32 v86, -1, v82
	v_fma_f32 v88, -v86, v82, v6
	v_add_u32_e32 v87, 1, v82
	v_cmp_ge_f32_e64 s[44:45], 0, v88
	v_add_f32_e32 v4, v4, v12
	v_fmamk_f32 v4, v4, 0x3b000000, v1
	v_cndmask_b32_e64 v86, v82, v86, s[44:45]
	v_fma_f32 v82, -v87, v82, v6
	v_cmp_lt_f32_e64 s[44:45], 0, v82
	v_add_f32_e32 v5, v5, v13
	v_fmamk_f32 v5, v5, 0x3b000000, v1
	v_cndmask_b32_e64 v82, v86, v87, s[44:45]
	v_mul_f32_e32 v86, 0x37800000, v82
	v_cndmask_b32_e32 v82, v82, v86, vcc
	v_cmp_class_f32_e32 vcc, v6, v226
	s_nop 1
	v_cndmask_b32_e32 v6, v82, v6, vcc
	v_div_scale_f32 v82, s[6:7], v6, v6, 1.0
	v_rcp_f32_e32 v86, v82
	s_nop 0
	v_fma_f32 v87, -v82, v86, 1.0
	v_fmac_f32_e32 v86, v87, v86
	v_div_scale_f32 v87, vcc, 1.0, v6, 1.0
	v_mul_f32_e32 v88, v87, v86
	v_fma_f32 v89, -v82, v88, v87
	v_fmac_f32_e32 v88, v89, v86
	v_fma_f32 v82, -v82, v88, v87
	v_div_fmas_f32 v82, v82, v86, v88
	v_div_fixup_f32 v6, v82, v6, 1.0
	v_pk_mul_f32 v[70:71], v[70:71], v[6:7] op_sel_hi:[1,0]
	v_pk_mul_f32 v[68:69], v[68:69], v[6:7] op_sel_hi:[1,0]
	v_and_b32_sdwa v6, v71, v228 dst_sel:DWORD dst_unused:UNUSED_PAD src0_sel:WORD_1 src1_sel:DWORD
	v_add_f32_e32 v7, v7, v83
	v_add3_u32 v6, v71, v6, s67
	v_and_b32_sdwa v71, v69, v228 dst_sel:DWORD dst_unused:UNUSED_PAD src0_sel:WORD_1 src1_sel:DWORD
	v_fmamk_f32 v7, v7, 0x3b000000, v1
	v_add3_u32 v69, v69, v71, s67
	v_mul_f32_e32 v71, 0x4f800000, v7
	v_cmp_gt_f32_e32 vcc, s70, v7
	v_and_b32_sdwa v82, v70, v228 dst_sel:DWORD dst_unused:UNUSED_PAD src0_sel:WORD_1 src1_sel:DWORD
	v_add3_u32 v70, v70, v82, s67
	v_cndmask_b32_e32 v7, v7, v71, vcc
	v_sqrt_f32_e32 v71, v7
	v_and_b32_sdwa v82, v68, v228 dst_sel:DWORD dst_unused:UNUSED_PAD src0_sel:WORD_1 src1_sel:DWORD
	v_add3_u32 v68, v68, v82, s67
	v_and_b32_e32 v69, 0xffff0000, v69
	v_and_b32_e32 v68, 0xffff0000, v68
	v_or_b32_sdwa v69, v69, v6 dst_sel:DWORD dst_unused:UNUSED_PAD src0_sel:DWORD src1_sel:WORD_1
	v_add_u32_e32 v6, -1, v71
	v_or_b32_sdwa v68, v68, v70 dst_sel:DWORD dst_unused:UNUSED_PAD src0_sel:DWORD src1_sel:WORD_1
	v_fma_f32 v70, -v6, v71, v7
	v_cmp_ge_f32_e64 s[44:45], 0, v70
	v_add_u32_e32 v70, 1, v71
	s_nop 0
	v_cndmask_b32_e64 v6, v71, v6, s[44:45]
	v_fma_f32 v71, -v70, v71, v7
	v_cmp_lt_f32_e64 s[44:45], 0, v71
	s_nop 1
	v_cndmask_b32_e64 v6, v6, v70, s[44:45]
	v_mul_f32_e32 v70, 0x37800000, v6
	v_cndmask_b32_e32 v6, v6, v70, vcc
	v_cmp_class_f32_e32 vcc, v7, v226
	s_nop 1
	v_cndmask_b32_e32 v70, v6, v7, vcc
	v_div_scale_f32 v71, s[6:7], v70, v70, 1.0
	v_rcp_f32_e32 v82, v71
	v_lshlrev_b64 v[6:7], 12, v[14:15]
	v_lshl_add_u64 v[6:7], v[36:37], 0, v[6:7]
	global_store_dwordx2 v[6:7], v[68:69], off nt
	v_fma_f32 v14, -v71, v82, 1.0
	v_fmac_f32_e32 v82, v14, v82
	v_div_scale_f32 v14, vcc, 1.0, v70, 1.0
	v_mul_f32_e32 v15, v14, v82
	v_fma_f32 v68, -v71, v15, v14
	v_fmac_f32_e32 v15, v68, v82
	v_fma_f32 v14, -v71, v15, v14
	v_div_fmas_f32 v14, v14, v82, v15
	v_div_fixup_f32 v14, v14, v70, 1.0
	v_pk_mul_f32 v[68:69], v[72:73], v[14:15] op_sel_hi:[1,0]
	v_pk_mul_f32 v[14:15], v[80:81], v[14:15] op_sel_hi:[1,0]
	v_and_b32_sdwa v70, v69, v228 dst_sel:DWORD dst_unused:UNUSED_PAD src0_sel:WORD_1 src1_sel:DWORD
	v_add3_u32 v69, v69, v70, s67
	v_and_b32_sdwa v70, v15, v228 dst_sel:DWORD dst_unused:UNUSED_PAD src0_sel:WORD_1 src1_sel:DWORD
	v_add3_u32 v15, v15, v70, s67
	v_mul_f32_e32 v70, 0x4f800000, v8
	v_cmp_gt_f32_e32 vcc, s70, v8
	v_and_b32_sdwa v71, v68, v228 dst_sel:DWORD dst_unused:UNUSED_PAD src0_sel:WORD_1 src1_sel:DWORD
	v_add3_u32 v68, v68, v71, s67
	v_cndmask_b32_e32 v8, v8, v70, vcc
	v_sqrt_f32_e32 v70, v8
	v_and_b32_sdwa v71, v14, v228 dst_sel:DWORD dst_unused:UNUSED_PAD src0_sel:WORD_1 src1_sel:DWORD
	v_add3_u32 v14, v14, v71, s67
	v_and_b32_e32 v14, 0xffff0000, v14
	v_and_b32_e32 v15, 0xffff0000, v15
	v_or_b32_sdwa v14, v14, v68 dst_sel:DWORD dst_unused:UNUSED_PAD src0_sel:DWORD src1_sel:WORD_1
	v_add_u32_e32 v68, -1, v70
	v_or_b32_sdwa v15, v15, v69 dst_sel:DWORD dst_unused:UNUSED_PAD src0_sel:DWORD src1_sel:WORD_1
	v_fma_f32 v69, -v68, v70, v8
	v_cmp_ge_f32_e64 s[44:45], 0, v69
	v_add_u32_e32 v69, 1, v70
	s_nop 0
	v_cndmask_b32_e64 v68, v70, v68, s[44:45]
	v_fma_f32 v70, -v69, v70, v8
	v_cmp_lt_f32_e64 s[44:45], 0, v70
	s_nop 1
	v_cndmask_b32_e64 v68, v68, v69, s[44:45]
	v_mul_f32_e32 v69, 0x37800000, v68
	v_cndmask_b32_e32 v68, v68, v69, vcc
	v_cmp_class_f32_e32 vcc, v8, v226
	s_nop 1
	v_cndmask_b32_e32 v8, v68, v8, vcc
	v_div_scale_f32 v70, s[6:7], v8, v8, 1.0
	v_rcp_f32_e32 v71, v70
	v_add_co_u32_e32 v68, vcc, s64, v6
	s_nop 1
	v_addc_co_u32_e32 v69, vcc, 0, v7, vcc
	global_store_dwordx2 v[68:69], v[14:15], off offset:-4096 nt
	v_fma_f32 v14, -v70, v71, 1.0
	v_fmac_f32_e32 v71, v14, v71
	v_div_scale_f32 v14, vcc, 1.0, v8, 1.0
	v_mul_f32_e32 v15, v14, v71
	v_fma_f32 v72, -v70, v15, v14
	v_fmac_f32_e32 v15, v72, v71
	v_fma_f32 v14, -v70, v15, v14
	v_div_fmas_f32 v14, v14, v71, v15
	v_div_fixup_f32 v8, v14, v8, 1.0
	v_pk_mul_f32 v[14:15], v[78:79], v[8:9] op_sel_hi:[1,0]
	v_pk_mul_f32 v[70:71], v[76:77], v[8:9] op_sel_hi:[1,0]
	v_and_b32_sdwa v8, v15, v228 dst_sel:DWORD dst_unused:UNUSED_PAD src0_sel:WORD_1 src1_sel:DWORD
	v_add_f32_e32 v9, v9, v85
	v_add3_u32 v8, v15, v8, s67
	v_and_b32_sdwa v15, v71, v228 dst_sel:DWORD dst_unused:UNUSED_PAD src0_sel:WORD_1 src1_sel:DWORD
	v_fmamk_f32 v9, v9, 0x3b000000, v1
	v_add3_u32 v15, v71, v15, s67
	v_mul_f32_e32 v71, 0x4f800000, v9
	v_cmp_gt_f32_e32 vcc, s70, v9
	v_and_b32_sdwa v72, v14, v228 dst_sel:DWORD dst_unused:UNUSED_PAD src0_sel:WORD_1 src1_sel:DWORD
	v_add3_u32 v14, v14, v72, s67
	v_cndmask_b32_e32 v9, v9, v71, vcc
	v_sqrt_f32_e32 v71, v9
	v_and_b32_sdwa v72, v70, v228 dst_sel:DWORD dst_unused:UNUSED_PAD src0_sel:WORD_1 src1_sel:DWORD
	v_add3_u32 v70, v70, v72, s67
	v_and_b32_e32 v15, 0xffff0000, v15
	v_add_u32_e32 v72, -1, v71
	v_fma_f32 v73, -v72, v71, v9
	v_cmp_ge_f32_e64 s[44:45], 0, v73
	v_add_u32_e32 v73, 1, v71
	v_and_b32_e32 v70, 0xffff0000, v70
	v_cndmask_b32_e64 v72, v71, v72, s[44:45]
	v_fma_f32 v71, -v73, v71, v9
	v_cmp_lt_f32_e64 s[44:45], 0, v71
	s_nop 1
	v_cndmask_b32_e64 v71, v72, v73, s[44:45]
	v_mul_f32_e32 v72, 0x37800000, v71
	v_cndmask_b32_e32 v71, v71, v72, vcc
	v_cmp_class_f32_e32 vcc, v9, v226
	s_nop 1
	v_cndmask_b32_e32 v71, v71, v9, vcc
	v_div_scale_f32 v72, s[6:7], v71, v71, 1.0
	v_rcp_f32_e32 v73, v72
	v_or_b32_sdwa v9, v15, v8 dst_sel:DWORD dst_unused:UNUSED_PAD src0_sel:DWORD src1_sel:WORD_1
	v_or_b32_sdwa v8, v70, v14 dst_sel:DWORD dst_unused:UNUSED_PAD src0_sel:DWORD src1_sel:WORD_1
	global_store_dwordx2 v[68:69], v[8:9], off nt
	v_fma_f32 v8, -v72, v73, 1.0
	v_fmac_f32_e32 v73, v8, v73
	v_div_scale_f32 v8, vcc, 1.0, v71, 1.0
	v_mul_f32_e32 v9, v8, v73
	v_fma_f32 v14, -v72, v9, v8
	v_fmac_f32_e32 v9, v14, v73
	v_fma_f32 v8, -v72, v9, v8
	v_div_fmas_f32 v8, v8, v73, v9
	v_div_fixup_f32 v8, v8, v71, 1.0
	v_cmp_gt_f32_e32 vcc, s70, v2
	v_pk_mul_f32 v[14:15], v[24:25], v[8:9] op_sel_hi:[1,0]
	v_pk_mul_f32 v[8:9], v[28:29], v[8:9] op_sel_hi:[1,0]
	v_cndmask_b32_e32 v2, v2, v10, vcc
	v_and_b32_sdwa v25, v14, v228 dst_sel:DWORD dst_unused:UNUSED_PAD src0_sel:WORD_1 src1_sel:DWORD
	v_sqrt_f32_e32 v10, v2
	v_and_b32_sdwa v24, v15, v228 dst_sel:DWORD dst_unused:UNUSED_PAD src0_sel:WORD_1 src1_sel:DWORD
	v_add3_u32 v14, v14, v25, s67
	v_and_b32_sdwa v25, v8, v228 dst_sel:DWORD dst_unused:UNUSED_PAD src0_sel:WORD_1 src1_sel:DWORD
	v_add3_u32 v15, v15, v24, s67
	v_and_b32_sdwa v24, v9, v228 dst_sel:DWORD dst_unused:UNUSED_PAD src0_sel:WORD_1 src1_sel:DWORD
	v_add3_u32 v8, v8, v25, s67
	v_add3_u32 v9, v9, v24, s67
	v_and_b32_e32 v8, 0xffff0000, v8
	v_and_b32_e32 v9, 0xffff0000, v9
	v_or_b32_sdwa v8, v8, v14 dst_sel:DWORD dst_unused:UNUSED_PAD src0_sel:DWORD src1_sel:WORD_1
	v_add_u32_e32 v14, -1, v10
	v_or_b32_sdwa v9, v9, v15 dst_sel:DWORD dst_unused:UNUSED_PAD src0_sel:DWORD src1_sel:WORD_1
	v_fma_f32 v15, -v14, v10, v2
	v_cmp_ge_f32_e64 s[44:45], 0, v15
	v_add_u32_e32 v15, 1, v10
	s_nop 0
	v_cndmask_b32_e64 v14, v10, v14, s[44:45]
	v_fma_f32 v10, -v15, v10, v2
	v_cmp_lt_f32_e64 s[44:45], 0, v10
	s_nop 1
	v_cndmask_b32_e64 v10, v14, v15, s[44:45]
	v_mul_f32_e32 v14, 0x37800000, v10
	v_cndmask_b32_e32 v10, v10, v14, vcc
	v_cmp_class_f32_e32 vcc, v2, v226
	s_nop 1
	v_cndmask_b32_e32 v2, v10, v2, vcc
	v_div_scale_f32 v10, s[6:7], v2, v2, 1.0
	v_rcp_f32_e32 v24, v10
	v_add_co_u32_e32 v14, vcc, s68, v6
	s_nop 1
	v_addc_co_u32_e32 v15, vcc, 0, v7, vcc
	global_store_dwordx2 v[14:15], v[8:9], off offset:-4096 nt
	v_fma_f32 v8, -v10, v24, 1.0
	v_fmac_f32_e32 v24, v8, v24
	v_div_scale_f32 v8, vcc, 1.0, v2, 1.0
	v_mul_f32_e32 v9, v8, v24
	v_fma_f32 v25, -v10, v9, v8
	v_fmac_f32_e32 v9, v25, v24
	v_fma_f32 v8, -v10, v9, v8
	v_div_fmas_f32 v8, v8, v24, v9
	v_div_fixup_f32 v2, v8, v2, 1.0
	v_pk_mul_f32 v[8:9], v[32:33], v[2:3] op_sel_hi:[1,0]
	v_pk_mul_f32 v[24:25], v[74:75], v[2:3] op_sel_hi:[1,0]
	v_add_f32_e32 v3, v3, v11
	v_fmamk_f32 v3, v3, 0x3b000000, v1
	v_mul_f32_e32 v11, 0x4f800000, v3
	v_cmp_gt_f32_e32 vcc, s70, v3
	v_and_b32_sdwa v10, v8, v228 dst_sel:DWORD dst_unused:UNUSED_PAD src0_sel:WORD_1 src1_sel:DWORD
	v_and_b32_sdwa v2, v9, v228 dst_sel:DWORD dst_unused:UNUSED_PAD src0_sel:WORD_1 src1_sel:DWORD
	v_cndmask_b32_e32 v3, v3, v11, vcc
	v_sqrt_f32_e32 v11, v3
	v_add3_u32 v8, v8, v10, s67
	v_and_b32_sdwa v10, v24, v228 dst_sel:DWORD dst_unused:UNUSED_PAD src0_sel:WORD_1 src1_sel:DWORD
	v_add3_u32 v2, v9, v2, s67
	v_and_b32_sdwa v9, v25, v228 dst_sel:DWORD dst_unused:UNUSED_PAD src0_sel:WORD_1 src1_sel:DWORD
	v_add3_u32 v10, v24, v10, s67
	v_add_u32_e32 v24, -1, v11
	v_add3_u32 v9, v25, v9, s67
	v_fma_f32 v25, -v24, v11, v3
	v_cmp_ge_f32_e64 s[44:45], 0, v25
	v_add_u32_e32 v25, 1, v11
	v_and_b32_e32 v9, 0xffff0000, v9
	v_cndmask_b32_e64 v24, v11, v24, s[44:45]
	v_fma_f32 v11, -v25, v11, v3
	v_cmp_lt_f32_e64 s[44:45], 0, v11
	v_and_b32_e32 v10, 0xffff0000, v10
	s_nop 0
	v_cndmask_b32_e64 v11, v24, v25, s[44:45]
	v_mul_f32_e32 v24, 0x37800000, v11
	v_cndmask_b32_e32 v11, v11, v24, vcc
	v_cmp_class_f32_e32 vcc, v3, v226
	s_nop 1
	v_cndmask_b32_e32 v11, v11, v3, vcc
	v_div_scale_f32 v24, s[6:7], v11, v11, 1.0
	v_rcp_f32_e32 v25, v24
	v_or_b32_sdwa v3, v9, v2 dst_sel:DWORD dst_unused:UNUSED_PAD src0_sel:DWORD src1_sel:WORD_1
	v_or_b32_sdwa v2, v10, v8 dst_sel:DWORD dst_unused:UNUSED_PAD src0_sel:DWORD src1_sel:WORD_1
	global_store_dwordx2 v[14:15], v[2:3], off nt
	v_fma_f32 v2, -v24, v25, 1.0
	v_fmac_f32_e32 v25, v2, v25
	v_div_scale_f32 v2, vcc, 1.0, v11, 1.0
	v_mul_f32_e32 v3, v2, v25
	v_fma_f32 v8, -v24, v3, v2
	v_fmac_f32_e32 v3, v8, v25
	v_fma_f32 v2, -v24, v3, v2
	v_div_fmas_f32 v2, v2, v25, v3
	v_div_fixup_f32 v2, v2, v11, 1.0
	v_pk_mul_f32 v[8:9], v[20:21], v[2:3] op_sel_hi:[1,0]
	v_pk_mul_f32 v[2:3], v[16:17], v[2:3] op_sel_hi:[1,0]
	v_and_b32_sdwa v10, v9, v228 dst_sel:DWORD dst_unused:UNUSED_PAD src0_sel:WORD_1 src1_sel:DWORD
	v_add3_u32 v9, v9, v10, s67
	v_and_b32_sdwa v10, v3, v228 dst_sel:DWORD dst_unused:UNUSED_PAD src0_sel:WORD_1 src1_sel:DWORD
	v_add3_u32 v3, v3, v10, s67
	v_mul_f32_e32 v10, 0x4f800000, v4
	v_cmp_gt_f32_e32 vcc, s70, v4
	v_and_b32_sdwa v11, v8, v228 dst_sel:DWORD dst_unused:UNUSED_PAD src0_sel:WORD_1 src1_sel:DWORD
	v_add3_u32 v8, v8, v11, s67
	v_cndmask_b32_e32 v4, v4, v10, vcc
	v_sqrt_f32_e32 v10, v4
	v_and_b32_sdwa v11, v2, v228 dst_sel:DWORD dst_unused:UNUSED_PAD src0_sel:WORD_1 src1_sel:DWORD
	v_add3_u32 v2, v2, v11, s67
	v_and_b32_e32 v2, 0xffff0000, v2
	v_and_b32_e32 v3, 0xffff0000, v3
	v_or_b32_sdwa v2, v2, v8 dst_sel:DWORD dst_unused:UNUSED_PAD src0_sel:DWORD src1_sel:WORD_1
	v_add_u32_e32 v8, -1, v10
	v_or_b32_sdwa v3, v3, v9 dst_sel:DWORD dst_unused:UNUSED_PAD src0_sel:DWORD src1_sel:WORD_1
	v_fma_f32 v9, -v8, v10, v4
	v_cmp_ge_f32_e64 s[44:45], 0, v9
	v_add_u32_e32 v9, 1, v10
	s_nop 0
	v_cndmask_b32_e64 v8, v10, v8, s[44:45]
	v_fma_f32 v10, -v9, v10, v4
	v_cmp_lt_f32_e64 s[44:45], 0, v10
	s_nop 1
	v_cndmask_b32_e64 v8, v8, v9, s[44:45]
	v_mul_f32_e32 v9, 0x37800000, v8
	v_cndmask_b32_e32 v8, v8, v9, vcc
	v_cmp_class_f32_e32 vcc, v4, v226
	s_nop 1
	v_cndmask_b32_e32 v4, v8, v4, vcc
	v_div_scale_f32 v10, s[6:7], v4, v4, 1.0
	v_rcp_f32_e32 v11, v10
	v_add_co_u32_e32 v8, vcc, s69, v6
	s_nop 1
	v_addc_co_u32_e32 v9, vcc, 0, v7, vcc
	global_store_dwordx2 v[8:9], v[2:3], off offset:-4096 nt
	v_fma_f32 v2, -v10, v11, 1.0
	v_fmac_f32_e32 v11, v2, v11
	v_div_scale_f32 v2, vcc, 1.0, v4, 1.0
	v_mul_f32_e32 v3, v2, v11
	v_fma_f32 v12, -v10, v3, v2
	v_fmac_f32_e32 v3, v12, v11
	v_fma_f32 v2, -v10, v3, v2
	v_div_fmas_f32 v2, v2, v11, v3
	v_div_fixup_f32 v2, v2, v4, 1.0
	v_pk_mul_f32 v[10:11], v[18:19], v[2:3] op_sel_hi:[1,0]
	v_pk_mul_f32 v[2:3], v[22:23], v[2:3] op_sel_hi:[1,0]
	v_and_b32_sdwa v4, v11, v228 dst_sel:DWORD dst_unused:UNUSED_PAD src0_sel:WORD_1 src1_sel:DWORD
	v_add3_u32 v4, v11, v4, s67
	v_and_b32_sdwa v11, v3, v228 dst_sel:DWORD dst_unused:UNUSED_PAD src0_sel:WORD_1 src1_sel:DWORD
	v_add3_u32 v3, v3, v11, s67
	v_mul_f32_e32 v11, 0x4f800000, v5
	v_cmp_gt_f32_e32 vcc, s70, v5
	v_and_b32_sdwa v12, v10, v228 dst_sel:DWORD dst_unused:UNUSED_PAD src0_sel:WORD_1 src1_sel:DWORD
	v_add3_u32 v10, v10, v12, s67
	v_cndmask_b32_e32 v5, v5, v11, vcc
	v_sqrt_f32_e32 v11, v5
	v_and_b32_sdwa v12, v2, v228 dst_sel:DWORD dst_unused:UNUSED_PAD src0_sel:WORD_1 src1_sel:DWORD
	v_add3_u32 v2, v2, v12, s67
	v_and_b32_e32 v3, 0xffff0000, v3
	v_add_u32_e32 v12, -1, v11
	v_fma_f32 v13, -v12, v11, v5
	v_cmp_ge_f32_e64 s[44:45], 0, v13
	v_add_u32_e32 v13, 1, v11
	v_and_b32_e32 v2, 0xffff0000, v2
	v_cndmask_b32_e64 v12, v11, v12, s[44:45]
	v_fma_f32 v11, -v13, v11, v5
	v_cmp_lt_f32_e64 s[44:45], 0, v11
	v_or_b32_sdwa v3, v3, v4 dst_sel:DWORD dst_unused:UNUSED_PAD src0_sel:DWORD src1_sel:WORD_1
	v_or_b32_sdwa v2, v2, v10 dst_sel:DWORD dst_unused:UNUSED_PAD src0_sel:DWORD src1_sel:WORD_1
	v_cndmask_b32_e64 v11, v12, v13, s[44:45]
	v_mul_f32_e32 v12, 0x37800000, v11
	v_cndmask_b32_e32 v11, v11, v12, vcc
	v_cmp_class_f32_e32 vcc, v5, v226
	global_store_dwordx2 v[8:9], v[2:3], off nt
	s_nop 0
	v_cndmask_b32_e32 v5, v11, v5, vcc
	v_div_scale_f32 v11, s[6:7], v5, v5, 1.0
	v_rcp_f32_e32 v12, v11
	s_nop 0
	v_fma_f32 v2, -v11, v12, 1.0
	v_fmac_f32_e32 v12, v2, v12
	v_div_scale_f32 v2, vcc, 1.0, v5, 1.0
	v_mul_f32_e32 v3, v2, v12
	v_fma_f32 v4, -v11, v3, v2
	v_fmac_f32_e32 v3, v4, v12
	v_fma_f32 v2, -v11, v3, v2
	v_div_fmas_f32 v2, v2, v12, v3
	v_div_fixup_f32 v2, v2, v5, 1.0
	v_pk_mul_f32 v[4:5], v[26:27], v[2:3] op_sel_hi:[1,0]
	v_pk_mul_f32 v[2:3], v[30:31], v[2:3] op_sel_hi:[1,0]
	v_and_b32_sdwa v9, v4, v228 dst_sel:DWORD dst_unused:UNUSED_PAD src0_sel:WORD_1 src1_sel:DWORD
	v_and_b32_sdwa v8, v5, v228 dst_sel:DWORD dst_unused:UNUSED_PAD src0_sel:WORD_1 src1_sel:DWORD
	v_add3_u32 v4, v4, v9, s67
	v_and_b32_sdwa v9, v2, v228 dst_sel:DWORD dst_unused:UNUSED_PAD src0_sel:WORD_1 src1_sel:DWORD
	v_add3_u32 v5, v5, v8, s67
	v_and_b32_sdwa v8, v3, v228 dst_sel:DWORD dst_unused:UNUSED_PAD src0_sel:WORD_1 src1_sel:DWORD
	v_add3_u32 v2, v2, v9, s67
	v_add3_u32 v3, v3, v8, s67
	v_and_b32_e32 v2, 0xffff0000, v2
	v_and_b32_e32 v3, 0xffff0000, v3
	v_or_b32_sdwa v2, v2, v4 dst_sel:DWORD dst_unused:UNUSED_PAD src0_sel:DWORD src1_sel:WORD_1
	v_add_co_u32_e32 v4, vcc, 0x7000, v6
	v_or_b32_sdwa v3, v3, v5 dst_sel:DWORD dst_unused:UNUSED_PAD src0_sel:DWORD src1_sel:WORD_1
	s_nop 0
	v_addc_co_u32_e32 v5, vcc, 0, v7, vcc
	global_store_dwordx2 v[4:5], v[2:3], off nt
	s_barrier
	s_branch .LBB0_602

.LBB0_808:
	s_or_b64 exec, exec, s[6:7]
	v_mov_b32_e32 v10, s4
	s_waitcnt lgkmcnt(0)
	s_barrier
	ds_read_b128 v[60:63], v10
	ds_read_b128 v[10:13], v10 offset:16
	s_add_i32 s25, s25, s24
	s_add_i32 s8, s8, s9
	s_cmpk_gt_i32 s25, 0x5ff
	s_waitcnt lgkmcnt(1)
	v_add_f32_e32 v6, v6, v60
	v_fmamk_f32 v6, v6, 0x3b000000, v1
	v_mul_f32_e32 v59, 0x4f800000, v6
	v_cmp_gt_f32_e32 vcc, s70, v6
	v_add_f32_e32 v8, v8, v62
	v_fmamk_f32 v8, v8, 0x3b000000, v1
	v_cndmask_b32_e32 v6, v6, v59, vcc
	v_sqrt_f32_e32 v59, v6
	s_waitcnt lgkmcnt(0)
	v_add_f32_e32 v2, v2, v10
	v_fmamk_f32 v2, v2, 0x3b000000, v1
	v_mul_f32_e32 v10, 0x4f800000, v2
	v_add_u32_e32 v60, -1, v59
	v_fma_f32 v65, -v60, v59, v6
	v_add_u32_e32 v64, 1, v59
	v_cmp_ge_f32_e64 s[38:39], 0, v65
	v_add_f32_e32 v4, v4, v12
	v_fmamk_f32 v4, v4, 0x3b000000, v1
	v_cndmask_b32_e64 v60, v59, v60, s[38:39]
	v_fma_f32 v59, -v64, v59, v6
	v_cmp_lt_f32_e64 s[38:39], 0, v59
	v_add_f32_e32 v5, v5, v13
	v_fmamk_f32 v5, v5, 0x3b000000, v1
	v_cndmask_b32_e64 v59, v60, v64, s[38:39]
	v_mul_f32_e32 v60, 0x37800000, v59
	v_cndmask_b32_e32 v59, v59, v60, vcc
	v_cmp_class_f32_e32 vcc, v6, v226
	s_nop 1
	v_cndmask_b32_e32 v6, v59, v6, vcc
	v_div_scale_f32 v59, s[6:7], v6, v6, 1.0
	v_rcp_f32_e32 v60, v59
	s_nop 0
	v_fma_f32 v64, -v59, v60, 1.0
	v_fmac_f32_e32 v60, v64, v60
	v_div_scale_f32 v64, vcc, 1.0, v6, 1.0
	v_mul_f32_e32 v65, v64, v60
	v_fma_f32 v66, -v59, v65, v64
	v_fmac_f32_e32 v65, v66, v60
	v_fma_f32 v59, -v59, v65, v64
	v_div_fmas_f32 v59, v59, v60, v65
	v_div_fixup_f32 v6, v59, v6, 1.0
	v_pk_mul_f32 v[34:35], v[34:35], v[6:7] op_sel_hi:[1,0]
	v_pk_mul_f32 v[36:37], v[36:37], v[6:7] op_sel_hi:[1,0]
	v_and_b32_sdwa v6, v35, v228 dst_sel:DWORD dst_unused:UNUSED_PAD src0_sel:WORD_1 src1_sel:DWORD
	v_add_f32_e32 v7, v7, v61
	v_add3_u32 v6, v35, v6, s67
	v_and_b32_sdwa v35, v37, v228 dst_sel:DWORD dst_unused:UNUSED_PAD src0_sel:WORD_1 src1_sel:DWORD
	v_fmamk_f32 v7, v7, 0x3b000000, v1
	v_add3_u32 v35, v37, v35, s67
	v_mul_f32_e32 v37, 0x4f800000, v7
	v_cmp_gt_f32_e32 vcc, s70, v7
	v_and_b32_sdwa v59, v34, v228 dst_sel:DWORD dst_unused:UNUSED_PAD src0_sel:WORD_1 src1_sel:DWORD
	v_add3_u32 v34, v34, v59, s67
	v_cndmask_b32_e32 v7, v7, v37, vcc
	v_sqrt_f32_e32 v37, v7
	v_and_b32_sdwa v59, v36, v228 dst_sel:DWORD dst_unused:UNUSED_PAD src0_sel:WORD_1 src1_sel:DWORD
	v_add3_u32 v36, v36, v59, s67
	v_and_b32_e32 v35, 0xffff0000, v35
	v_and_b32_e32 v36, 0xffff0000, v36
	v_or_b32_sdwa v35, v35, v6 dst_sel:DWORD dst_unused:UNUSED_PAD src0_sel:DWORD src1_sel:WORD_1
	v_add_u32_e32 v6, -1, v37
	v_or_b32_sdwa v34, v36, v34 dst_sel:DWORD dst_unused:UNUSED_PAD src0_sel:DWORD src1_sel:WORD_1
	v_fma_f32 v36, -v6, v37, v7
	v_cmp_ge_f32_e64 s[38:39], 0, v36
	v_add_u32_e32 v36, 1, v37
	s_nop 0
	v_cndmask_b32_e64 v6, v37, v6, s[38:39]
	v_fma_f32 v37, -v36, v37, v7
	v_cmp_lt_f32_e64 s[38:39], 0, v37
	s_nop 1
	v_cndmask_b32_e64 v6, v6, v36, s[38:39]
	v_mul_f32_e32 v36, 0x37800000, v6
	v_cndmask_b32_e32 v6, v6, v36, vcc
	v_cmp_class_f32_e32 vcc, v7, v226
	s_nop 1
	v_cndmask_b32_e32 v36, v6, v7, vcc
	v_div_scale_f32 v37, s[6:7], v36, v36, 1.0
	v_rcp_f32_e32 v59, v37
	v_lshlrev_b64 v[6:7], 12, v[28:29]
	v_lshl_add_u64 v[6:7], v[26:27], 0, v[6:7]
	global_store_dwordx2 v[6:7], v[34:35], off nt
	v_fma_f32 v28, -v37, v59, 1.0
	v_fmac_f32_e32 v59, v28, v59
	v_div_scale_f32 v28, vcc, 1.0, v36, 1.0
	v_mul_f32_e32 v29, v28, v59
	v_fma_f32 v34, -v37, v29, v28
	v_fmac_f32_e32 v29, v34, v59
	v_fma_f32 v28, -v37, v29, v28
	v_div_fmas_f32 v28, v28, v59, v29
	v_div_fixup_f32 v28, v28, v36, 1.0
	v_pk_mul_f32 v[34:35], v[38:39], v[28:29] op_sel_hi:[1,0]
	v_pk_mul_f32 v[28:29], v[40:41], v[28:29] op_sel_hi:[1,0]
	v_and_b32_sdwa v36, v35, v228 dst_sel:DWORD dst_unused:UNUSED_PAD src0_sel:WORD_1 src1_sel:DWORD
	v_add3_u32 v35, v35, v36, s67
	v_and_b32_sdwa v36, v29, v228 dst_sel:DWORD dst_unused:UNUSED_PAD src0_sel:WORD_1 src1_sel:DWORD
	v_add3_u32 v29, v29, v36, s67
	v_mul_f32_e32 v36, 0x4f800000, v8
	v_cmp_gt_f32_e32 vcc, s70, v8
	v_and_b32_sdwa v37, v34, v228 dst_sel:DWORD dst_unused:UNUSED_PAD src0_sel:WORD_1 src1_sel:DWORD
	v_add3_u32 v34, v34, v37, s67
	v_cndmask_b32_e32 v8, v8, v36, vcc
	v_sqrt_f32_e32 v36, v8
	v_and_b32_sdwa v37, v28, v228 dst_sel:DWORD dst_unused:UNUSED_PAD src0_sel:WORD_1 src1_sel:DWORD
	v_add3_u32 v28, v28, v37, s67
	v_and_b32_e32 v28, 0xffff0000, v28
	v_and_b32_e32 v29, 0xffff0000, v29
	v_or_b32_sdwa v28, v28, v34 dst_sel:DWORD dst_unused:UNUSED_PAD src0_sel:DWORD src1_sel:WORD_1
	v_add_u32_e32 v34, -1, v36
	v_or_b32_sdwa v29, v29, v35 dst_sel:DWORD dst_unused:UNUSED_PAD src0_sel:DWORD src1_sel:WORD_1
	v_fma_f32 v35, -v34, v36, v8
	v_cmp_ge_f32_e64 s[38:39], 0, v35
	v_add_u32_e32 v35, 1, v36
	s_nop 0
	v_cndmask_b32_e64 v34, v36, v34, s[38:39]
	v_fma_f32 v36, -v35, v36, v8
	v_cmp_lt_f32_e64 s[38:39], 0, v36
	s_nop 1
	v_cndmask_b32_e64 v34, v34, v35, s[38:39]
	v_mul_f32_e32 v35, 0x37800000, v34
	v_cndmask_b32_e32 v34, v34, v35, vcc
	v_cmp_class_f32_e32 vcc, v8, v226
	s_nop 1
	v_cndmask_b32_e32 v8, v34, v8, vcc
	v_div_scale_f32 v36, s[6:7], v8, v8, 1.0
	v_rcp_f32_e32 v37, v36
	v_add_co_u32_e32 v34, vcc, s64, v6
	s_nop 1
	v_addc_co_u32_e32 v35, vcc, 0, v7, vcc
	global_store_dwordx2 v[34:35], v[28:29], off offset:-4096 nt
	v_fma_f32 v28, -v36, v37, 1.0
	v_fmac_f32_e32 v37, v28, v37
	v_div_scale_f32 v28, vcc, 1.0, v8, 1.0
	v_mul_f32_e32 v29, v28, v37
	v_fma_f32 v38, -v36, v29, v28
	v_fmac_f32_e32 v29, v38, v37
	v_fma_f32 v28, -v36, v29, v28
	v_div_fmas_f32 v28, v28, v37, v29
	v_div_fixup_f32 v8, v28, v8, 1.0
	v_pk_mul_f32 v[28:29], v[30:31], v[8:9] op_sel_hi:[1,0]
	v_pk_mul_f32 v[30:31], v[32:33], v[8:9] op_sel_hi:[1,0]
	v_and_b32_sdwa v8, v29, v228 dst_sel:DWORD dst_unused:UNUSED_PAD src0_sel:WORD_1 src1_sel:DWORD
	v_add_f32_e32 v9, v9, v63
	v_add3_u32 v8, v29, v8, s67
	v_and_b32_sdwa v29, v31, v228 dst_sel:DWORD dst_unused:UNUSED_PAD src0_sel:WORD_1 src1_sel:DWORD
	v_fmamk_f32 v9, v9, 0x3b000000, v1
	v_add3_u32 v29, v31, v29, s67
	v_mul_f32_e32 v31, 0x4f800000, v9
	v_cmp_gt_f32_e32 vcc, s70, v9
	v_and_b32_sdwa v32, v28, v228 dst_sel:DWORD dst_unused:UNUSED_PAD src0_sel:WORD_1 src1_sel:DWORD
	v_add3_u32 v28, v28, v32, s67
	v_cndmask_b32_e32 v9, v9, v31, vcc
	v_sqrt_f32_e32 v31, v9
	v_and_b32_sdwa v32, v30, v228 dst_sel:DWORD dst_unused:UNUSED_PAD src0_sel:WORD_1 src1_sel:DWORD
	v_add3_u32 v30, v30, v32, s67
	v_and_b32_e32 v29, 0xffff0000, v29
	v_add_u32_e32 v32, -1, v31
	v_fma_f32 v33, -v32, v31, v9
	v_cmp_ge_f32_e64 s[38:39], 0, v33
	v_add_u32_e32 v33, 1, v31
	v_and_b32_e32 v30, 0xffff0000, v30
	v_cndmask_b32_e64 v32, v31, v32, s[38:39]
	v_fma_f32 v31, -v33, v31, v9
	v_cmp_lt_f32_e64 s[38:39], 0, v31
	s_nop 1
	v_cndmask_b32_e64 v31, v32, v33, s[38:39]
	v_mul_f32_e32 v32, 0x37800000, v31
	v_cndmask_b32_e32 v31, v31, v32, vcc
	v_cmp_class_f32_e32 vcc, v9, v226
	s_nop 1
	v_cndmask_b32_e32 v31, v31, v9, vcc
	v_div_scale_f32 v32, s[6:7], v31, v31, 1.0
	v_rcp_f32_e32 v33, v32
	v_or_b32_sdwa v9, v29, v8 dst_sel:DWORD dst_unused:UNUSED_PAD src0_sel:DWORD src1_sel:WORD_1
	v_or_b32_sdwa v8, v30, v28 dst_sel:DWORD dst_unused:UNUSED_PAD src0_sel:DWORD src1_sel:WORD_1
	global_store_dwordx2 v[34:35], v[8:9], off nt
	v_fma_f32 v8, -v32, v33, 1.0
	v_fmac_f32_e32 v33, v8, v33
	v_div_scale_f32 v8, vcc, 1.0, v31, 1.0
	v_mul_f32_e32 v9, v8, v33
	v_fma_f32 v28, -v32, v9, v8
	v_fmac_f32_e32 v9, v28, v33
	v_fma_f32 v8, -v32, v9, v8
	v_div_fmas_f32 v8, v8, v33, v9
	v_div_fixup_f32 v8, v8, v31, 1.0
	v_cmp_gt_f32_e32 vcc, s70, v2
	v_pk_mul_f32 v[14:15], v[14:15], v[8:9] op_sel_hi:[1,0]
	v_pk_mul_f32 v[8:9], v[42:43], v[8:9] op_sel_hi:[1,0]
	v_cndmask_b32_e32 v2, v2, v10, vcc
	v_and_b32_sdwa v29, v14, v228 dst_sel:DWORD dst_unused:UNUSED_PAD src0_sel:WORD_1 src1_sel:DWORD
	v_sqrt_f32_e32 v10, v2
	v_and_b32_sdwa v28, v15, v228 dst_sel:DWORD dst_unused:UNUSED_PAD src0_sel:WORD_1 src1_sel:DWORD
	v_add3_u32 v14, v14, v29, s67
	v_and_b32_sdwa v29, v8, v228 dst_sel:DWORD dst_unused:UNUSED_PAD src0_sel:WORD_1 src1_sel:DWORD
	v_add3_u32 v15, v15, v28, s67
	v_and_b32_sdwa v28, v9, v228 dst_sel:DWORD dst_unused:UNUSED_PAD src0_sel:WORD_1 src1_sel:DWORD
	v_add3_u32 v8, v8, v29, s67
	v_add3_u32 v9, v9, v28, s67
	v_and_b32_e32 v8, 0xffff0000, v8
	v_and_b32_e32 v9, 0xffff0000, v9
	v_or_b32_sdwa v8, v8, v14 dst_sel:DWORD dst_unused:UNUSED_PAD src0_sel:DWORD src1_sel:WORD_1
	v_add_u32_e32 v14, -1, v10
	v_or_b32_sdwa v9, v9, v15 dst_sel:DWORD dst_unused:UNUSED_PAD src0_sel:DWORD src1_sel:WORD_1
	v_fma_f32 v15, -v14, v10, v2
	v_cmp_ge_f32_e64 s[38:39], 0, v15
	v_add_u32_e32 v15, 1, v10
	s_nop 0
	v_cndmask_b32_e64 v14, v10, v14, s[38:39]
	v_fma_f32 v10, -v15, v10, v2
	v_cmp_lt_f32_e64 s[38:39], 0, v10
	s_nop 1
	v_cndmask_b32_e64 v10, v14, v15, s[38:39]
	v_mul_f32_e32 v14, 0x37800000, v10
	v_cndmask_b32_e32 v10, v10, v14, vcc
	v_cmp_class_f32_e32 vcc, v2, v226
	s_nop 1
	v_cndmask_b32_e32 v2, v10, v2, vcc
	v_div_scale_f32 v10, s[6:7], v2, v2, 1.0
	v_rcp_f32_e32 v28, v10
	v_add_co_u32_e32 v14, vcc, s68, v6
	s_nop 1
	v_addc_co_u32_e32 v15, vcc, 0, v7, vcc
	global_store_dwordx2 v[14:15], v[8:9], off offset:-4096 nt
	v_fma_f32 v8, -v10, v28, 1.0
	v_fmac_f32_e32 v28, v8, v28
	v_div_scale_f32 v8, vcc, 1.0, v2, 1.0
	v_mul_f32_e32 v9, v8, v28
	v_fma_f32 v29, -v10, v9, v8
	v_fmac_f32_e32 v9, v29, v28
	v_fma_f32 v8, -v10, v9, v8
	v_div_fmas_f32 v8, v8, v28, v9
	v_div_fixup_f32 v2, v8, v2, 1.0
	v_pk_mul_f32 v[8:9], v[44:45], v[2:3] op_sel_hi:[1,0]
	v_pk_mul_f32 v[28:29], v[46:47], v[2:3] op_sel_hi:[1,0]
	v_add_f32_e32 v3, v3, v11
	v_fmamk_f32 v3, v3, 0x3b000000, v1
	v_mul_f32_e32 v11, 0x4f800000, v3
	v_cmp_gt_f32_e32 vcc, s70, v3
	v_and_b32_sdwa v10, v8, v228 dst_sel:DWORD dst_unused:UNUSED_PAD src0_sel:WORD_1 src1_sel:DWORD
	v_and_b32_sdwa v2, v9, v228 dst_sel:DWORD dst_unused:UNUSED_PAD src0_sel:WORD_1 src1_sel:DWORD
	v_cndmask_b32_e32 v3, v3, v11, vcc
	v_sqrt_f32_e32 v11, v3
	v_add3_u32 v8, v8, v10, s67
	v_and_b32_sdwa v10, v28, v228 dst_sel:DWORD dst_unused:UNUSED_PAD src0_sel:WORD_1 src1_sel:DWORD
	v_add3_u32 v2, v9, v2, s67
	v_and_b32_sdwa v9, v29, v228 dst_sel:DWORD dst_unused:UNUSED_PAD src0_sel:WORD_1 src1_sel:DWORD
	v_add3_u32 v10, v28, v10, s67
	v_add_u32_e32 v28, -1, v11
	v_add3_u32 v9, v29, v9, s67
	v_fma_f32 v29, -v28, v11, v3
	v_cmp_ge_f32_e64 s[38:39], 0, v29
	v_add_u32_e32 v29, 1, v11
	v_and_b32_e32 v9, 0xffff0000, v9
	v_cndmask_b32_e64 v28, v11, v28, s[38:39]
	v_fma_f32 v11, -v29, v11, v3
	v_cmp_lt_f32_e64 s[38:39], 0, v11
	v_and_b32_e32 v10, 0xffff0000, v10
	s_nop 0
	v_cndmask_b32_e64 v11, v28, v29, s[38:39]
	v_mul_f32_e32 v28, 0x37800000, v11
	v_cndmask_b32_e32 v11, v11, v28, vcc
	v_cmp_class_f32_e32 vcc, v3, v226
	s_nop 1
	v_cndmask_b32_e32 v11, v11, v3, vcc
	v_div_scale_f32 v28, s[6:7], v11, v11, 1.0
	v_rcp_f32_e32 v29, v28
	v_or_b32_sdwa v3, v9, v2 dst_sel:DWORD dst_unused:UNUSED_PAD src0_sel:DWORD src1_sel:WORD_1
	v_or_b32_sdwa v2, v10, v8 dst_sel:DWORD dst_unused:UNUSED_PAD src0_sel:DWORD src1_sel:WORD_1
	global_store_dwordx2 v[14:15], v[2:3], off nt
	v_fma_f32 v2, -v28, v29, 1.0
	v_fmac_f32_e32 v29, v2, v29
	v_div_scale_f32 v2, vcc, 1.0, v11, 1.0
	v_mul_f32_e32 v3, v2, v29
	v_fma_f32 v8, -v28, v3, v2
	v_fmac_f32_e32 v3, v8, v29
	v_fma_f32 v2, -v28, v3, v2
	v_div_fmas_f32 v2, v2, v29, v3
	v_div_fixup_f32 v2, v2, v11, 1.0
	v_pk_mul_f32 v[8:9], v[52:53], v[2:3] op_sel_hi:[1,0]
	v_pk_mul_f32 v[2:3], v[54:55], v[2:3] op_sel_hi:[1,0]
	v_and_b32_sdwa v10, v9, v228 dst_sel:DWORD dst_unused:UNUSED_PAD src0_sel:WORD_1 src1_sel:DWORD
	v_add3_u32 v9, v9, v10, s67
	v_and_b32_sdwa v10, v3, v228 dst_sel:DWORD dst_unused:UNUSED_PAD src0_sel:WORD_1 src1_sel:DWORD
	v_add3_u32 v3, v3, v10, s67
	v_mul_f32_e32 v10, 0x4f800000, v4
	v_cmp_gt_f32_e32 vcc, s70, v4
	v_and_b32_sdwa v11, v8, v228 dst_sel:DWORD dst_unused:UNUSED_PAD src0_sel:WORD_1 src1_sel:DWORD
	v_add3_u32 v8, v8, v11, s67
	v_cndmask_b32_e32 v4, v4, v10, vcc
	v_sqrt_f32_e32 v10, v4
	v_and_b32_sdwa v11, v2, v228 dst_sel:DWORD dst_unused:UNUSED_PAD src0_sel:WORD_1 src1_sel:DWORD
	v_add3_u32 v2, v2, v11, s67
	v_and_b32_e32 v2, 0xffff0000, v2
	v_and_b32_e32 v3, 0xffff0000, v3
	v_or_b32_sdwa v2, v2, v8 dst_sel:DWORD dst_unused:UNUSED_PAD src0_sel:DWORD src1_sel:WORD_1
	v_add_u32_e32 v8, -1, v10
	v_or_b32_sdwa v3, v3, v9 dst_sel:DWORD dst_unused:UNUSED_PAD src0_sel:DWORD src1_sel:WORD_1
	v_fma_f32 v9, -v8, v10, v4
	v_cmp_ge_f32_e64 s[38:39], 0, v9
	v_add_u32_e32 v9, 1, v10
	s_nop 0
	v_cndmask_b32_e64 v8, v10, v8, s[38:39]
	v_fma_f32 v10, -v9, v10, v4
	v_cmp_lt_f32_e64 s[38:39], 0, v10
	s_nop 1
	v_cndmask_b32_e64 v8, v8, v9, s[38:39]
	v_mul_f32_e32 v9, 0x37800000, v8
	v_cndmask_b32_e32 v8, v8, v9, vcc
	v_cmp_class_f32_e32 vcc, v4, v226
	s_nop 1
	v_cndmask_b32_e32 v4, v8, v4, vcc
	v_div_scale_f32 v10, s[6:7], v4, v4, 1.0
	v_rcp_f32_e32 v11, v10
	v_add_co_u32_e32 v8, vcc, s69, v6
	s_nop 1
	v_addc_co_u32_e32 v9, vcc, 0, v7, vcc
	global_store_dwordx2 v[8:9], v[2:3], off offset:-4096 nt
	v_fma_f32 v2, -v10, v11, 1.0
	v_fmac_f32_e32 v11, v2, v11
	v_div_scale_f32 v2, vcc, 1.0, v4, 1.0
	v_mul_f32_e32 v3, v2, v11
	v_fma_f32 v12, -v10, v3, v2
	v_fmac_f32_e32 v3, v12, v11
	v_fma_f32 v2, -v10, v3, v2
	v_div_fmas_f32 v2, v2, v11, v3
	v_div_fixup_f32 v2, v2, v4, 1.0
	v_pk_mul_f32 v[10:11], v[48:49], v[2:3] op_sel_hi:[1,0]
	v_pk_mul_f32 v[2:3], v[50:51], v[2:3] op_sel_hi:[1,0]
	v_and_b32_sdwa v4, v11, v228 dst_sel:DWORD dst_unused:UNUSED_PAD src0_sel:WORD_1 src1_sel:DWORD
	v_add3_u32 v4, v11, v4, s67
	v_and_b32_sdwa v11, v3, v228 dst_sel:DWORD dst_unused:UNUSED_PAD src0_sel:WORD_1 src1_sel:DWORD
	v_add3_u32 v3, v3, v11, s67
	v_mul_f32_e32 v11, 0x4f800000, v5
	v_cmp_gt_f32_e32 vcc, s70, v5
	v_and_b32_sdwa v12, v10, v228 dst_sel:DWORD dst_unused:UNUSED_PAD src0_sel:WORD_1 src1_sel:DWORD
	v_add3_u32 v10, v10, v12, s67
	v_cndmask_b32_e32 v5, v5, v11, vcc
	v_sqrt_f32_e32 v11, v5
	v_and_b32_sdwa v12, v2, v228 dst_sel:DWORD dst_unused:UNUSED_PAD src0_sel:WORD_1 src1_sel:DWORD
	v_add3_u32 v2, v2, v12, s67
	v_and_b32_e32 v3, 0xffff0000, v3
	v_add_u32_e32 v12, -1, v11
	v_fma_f32 v13, -v12, v11, v5
	v_cmp_ge_f32_e64 s[38:39], 0, v13
	v_add_u32_e32 v13, 1, v11
	v_and_b32_e32 v2, 0xffff0000, v2
	v_cndmask_b32_e64 v12, v11, v12, s[38:39]
	v_fma_f32 v11, -v13, v11, v5
	v_cmp_lt_f32_e64 s[38:39], 0, v11
	v_or_b32_sdwa v3, v3, v4 dst_sel:DWORD dst_unused:UNUSED_PAD src0_sel:DWORD src1_sel:WORD_1
	v_or_b32_sdwa v2, v2, v10 dst_sel:DWORD dst_unused:UNUSED_PAD src0_sel:DWORD src1_sel:WORD_1
	v_cndmask_b32_e64 v11, v12, v13, s[38:39]
	v_mul_f32_e32 v12, 0x37800000, v11
	v_cndmask_b32_e32 v11, v11, v12, vcc
	v_cmp_class_f32_e32 vcc, v5, v226
	global_store_dwordx2 v[8:9], v[2:3], off nt
	s_nop 0
	v_cndmask_b32_e32 v5, v11, v5, vcc
	v_div_scale_f32 v11, s[6:7], v5, v5, 1.0
	v_rcp_f32_e32 v12, v11
	s_nop 0
	v_fma_f32 v2, -v11, v12, 1.0
	v_fmac_f32_e32 v12, v2, v12
	v_div_scale_f32 v2, vcc, 1.0, v5, 1.0
	v_mul_f32_e32 v3, v2, v12
	v_fma_f32 v4, -v11, v3, v2
	v_fmac_f32_e32 v3, v4, v12
	v_fma_f32 v2, -v11, v3, v2
	v_div_fmas_f32 v2, v2, v12, v3
	v_div_fixup_f32 v2, v2, v5, 1.0
	v_pk_mul_f32 v[4:5], v[16:17], v[2:3] op_sel_hi:[1,0]
	v_pk_mul_f32 v[2:3], v[56:57], v[2:3] op_sel_hi:[1,0]
	v_and_b32_sdwa v9, v4, v228 dst_sel:DWORD dst_unused:UNUSED_PAD src0_sel:WORD_1 src1_sel:DWORD
	v_and_b32_sdwa v8, v5, v228 dst_sel:DWORD dst_unused:UNUSED_PAD src0_sel:WORD_1 src1_sel:DWORD
	v_add3_u32 v4, v4, v9, s67
	v_and_b32_sdwa v9, v2, v228 dst_sel:DWORD dst_unused:UNUSED_PAD src0_sel:WORD_1 src1_sel:DWORD
	v_add3_u32 v5, v5, v8, s67
	v_and_b32_sdwa v8, v3, v228 dst_sel:DWORD dst_unused:UNUSED_PAD src0_sel:WORD_1 src1_sel:DWORD
	v_add3_u32 v2, v2, v9, s67
	v_add3_u32 v3, v3, v8, s67
	v_and_b32_e32 v2, 0xffff0000, v2
	v_and_b32_e32 v3, 0xffff0000, v3
	v_or_b32_sdwa v2, v2, v4 dst_sel:DWORD dst_unused:UNUSED_PAD src0_sel:DWORD src1_sel:WORD_1
	v_add_co_u32_e32 v4, vcc, 0x7000, v6
	v_or_b32_sdwa v3, v3, v5 dst_sel:DWORD dst_unused:UNUSED_PAD src0_sel:DWORD src1_sel:WORD_1
	s_nop 0
	v_addc_co_u32_e32 v5, vcc, 0, v7, vcc
	global_store_dwordx2 v[4:5], v[2:3], off nt
	s_barrier
	s_cbranch_scc1 .LBB0_811

.LBB0_1024:
	s_or_b64 exec, exec, s[20:21]
	v_div_scale_f32 v49, s[20:21], v5, v5, s47
	s_waitcnt lgkmcnt(0)
	v_rcp_f32_e32 v50, v49
	v_div_scale_f32 v51, vcc, s47, v5, s47
	s_add_i32 s1, s1, -1
	v_fma_f32 v52, -v49, v50, 1.0
	v_fmac_f32_e32 v50, v52, v50
	v_mul_f32_e32 v52, v51, v50
	v_fma_f32 v53, -v49, v52, v51
	v_fmac_f32_e32 v52, v53, v50
	v_fma_f32 v49, -v49, v52, v51
	v_div_fmas_f32 v49, v49, v50, v52
	v_div_fixup_f32 v5, v49, v5, s47
	v_mul_f32_e32 v47, v5, v47
	v_mul_f32_e32 v46, v5, v46
	v_mul_f32_e32 v48, v5, v48
	v_rndne_f32_e32 v47, v47
	v_rndne_f32_e32 v46, v46
	v_mul_f32_e32 v45, v5, v45
	v_rndne_f32_e32 v48, v48
	v_cvt_i32_f32_e32 v47, v47
	v_cvt_i32_f32_e32 v46, v46
	v_rndne_f32_e32 v45, v45
	v_mul_f32_e32 v43, v5, v43
	v_mul_f32_e32 v41, v5, v41
	v_cvt_i32_f32_e32 v48, v48
	v_cvt_i32_f32_e32 v45, v45
	v_mul_f32_e32 v44, v5, v44
	v_rndne_f32_e32 v43, v43
	v_rndne_f32_e32 v41, v41
	v_mul_f32_e32 v40, v5, v40
	v_rndne_f32_e32 v44, v44
	v_cvt_i32_f32_e32 v43, v43
	v_cvt_i32_f32_e32 v41, v41
	v_rndne_f32_e32 v40, v40
	v_cvt_i32_f32_e32 v49, v44
	v_cvt_i32_f32_e32 v40, v40
	v_med3_i32 v47, v47, s71, v235
	v_med3_i32 v46, v46, s71, v235
	v_mul_f32_e32 v38, v5, v38
	v_mul_f32_e32 v37, v5, v37
	v_med3_i32 v48, v48, s71, v235
	v_lshlrev_b32_e32 v47, 8, v47
	v_lshlrev_b32_e32 v46, 16, v46
	v_med3_i32 v45, v45, s71, v235
	v_mul_f32_e32 v39, v5, v39
	v_rndne_f32_e32 v38, v38
	v_rndne_f32_e32 v37, v37
	v_mul_f32_e32 v36, v5, v36
	v_and_b32_e32 v46, 0xff0000, v46
	v_lshlrev_b32_e32 v45, 24, v45
	v_perm_b32 v44, v47, v48, s49
	v_med3_i32 v43, v43, s71, v235
	v_med3_i32 v41, v41, s71, v235
	v_rndne_f32_e32 v39, v39
	v_cvt_i32_f32_e32 v38, v38
	v_cvt_i32_f32_e32 v37, v37
	v_rndne_f32_e32 v36, v36
	v_or3_b32 v44, v44, v45, v46
	v_med3_i32 v45, v49, s71, v235
	v_lshlrev_b32_e32 v43, 8, v43
	v_lshlrev_b32_e32 v41, 16, v41
	v_med3_i32 v40, v40, s71, v235
	v_cvt_i32_f32_e32 v39, v39
	v_cvt_i32_f32_e32 v36, v36
	v_mul_f32_e32 v34, v5, v34
	v_mul_f32_e32 v33, v5, v33
	v_and_b32_e32 v43, 0xff00, v43
	v_and_b32_e32 v41, 0xff0000, v41
	v_perm_b32 v40, v40, v45, s48
	v_mul_f32_e32 v35, v5, v35
	v_rndne_f32_e32 v34, v34
	v_rndne_f32_e32 v33, v33
	v_mul_f32_e32 v32, v5, v32
	v_or3_b32 v45, v40, v43, v41
	v_rndne_f32_e32 v35, v35
	v_cvt_i32_f32_e32 v40, v34
	v_cvt_i32_f32_e32 v33, v33
	v_rndne_f32_e32 v32, v32
	v_med3_i32 v38, v38, s71, v235
	v_med3_i32 v37, v37, s71, v235
	v_cvt_i32_f32_e32 v35, v35
	v_cvt_i32_f32_e32 v32, v32
	v_med3_i32 v39, v39, s71, v235
	v_lshlrev_b32_e32 v38, 8, v38
	v_lshlrev_b32_e32 v37, 16, v37
	v_med3_i32 v36, v36, s71, v235
	v_mul_f32_e32 v17, v5, v17
	v_mul_f32_e32 v16, v5, v16
	v_and_b32_e32 v37, 0xff0000, v37
	v_lshlrev_b32_e32 v36, 24, v36
	v_perm_b32 v34, v38, v39, s49
	v_mul_f32_e32 v31, v5, v31
	v_rndne_f32_e32 v17, v17
	v_rndne_f32_e32 v16, v16
	v_mul_f32_e32 v15, v5, v15
	v_or3_b32 v34, v34, v36, v37
	v_med3_i32 v36, v40, s71, v235
	v_med3_i32 v33, v33, s71, v235
	v_rndne_f32_e32 v31, v31
	v_cvt_i32_f32_e32 v17, v17
	v_cvt_i32_f32_e32 v16, v16
	v_rndne_f32_e32 v15, v15
	v_mul_f32_e32 v13, v5, v13
	v_mul_f32_e32 v12, v5, v12
	v_med3_i32 v35, v35, s71, v235
	v_lshlrev_b32_e32 v36, 8, v36
	v_lshlrev_b32_e32 v33, 16, v33
	v_med3_i32 v32, v32, s71, v235
	v_cvt_i32_f32_e32 v31, v31
	v_cvt_i32_f32_e32 v15, v15
	v_mul_f32_e32 v14, v5, v14
	v_rndne_f32_e32 v13, v13
	v_rndne_f32_e32 v12, v12
	v_mul_f32_e32 v11, v5, v11
	v_and_b32_e32 v36, 0xff00, v36
	v_and_b32_e32 v33, 0xff0000, v33
	v_perm_b32 v32, v32, v35, s48
	v_rndne_f32_e32 v14, v14
	v_cvt_i32_f32_e32 v13, v13
	v_cvt_i32_f32_e32 v12, v12
	v_rndne_f32_e32 v11, v11
	v_or3_b32 v35, v32, v36, v33
	v_cvt_i32_f32_e32 v32, v14
	v_cvt_i32_f32_e32 v11, v11
	v_med3_i32 v17, v17, s71, v235
	v_med3_i32 v16, v16, s71, v235
	v_mul_f32_e32 v9, v5, v9
	v_mul_f32_e32 v8, v5, v8
	v_med3_i32 v31, v31, s71, v235
	v_lshlrev_b32_e32 v17, 8, v17
	v_lshlrev_b32_e32 v16, 16, v16
	v_med3_i32 v15, v15, s71, v235
	v_mul_f32_e32 v10, v5, v10
	v_rndne_f32_e32 v9, v9
	v_rndne_f32_e32 v8, v8
	v_mul_f32_e32 v7, v5, v7
	v_and_b32_e32 v16, 0xff0000, v16
	v_lshlrev_b32_e32 v15, 24, v15
	v_perm_b32 v14, v17, v31, s49
	v_med3_i32 v13, v13, s71, v235
	v_med3_i32 v12, v12, s71, v235
	v_rndne_f32_e32 v10, v10
	v_cvt_i32_f32_e32 v9, v9
	v_cvt_i32_f32_e32 v8, v8
	v_rndne_f32_e32 v7, v7
	v_or3_b32 v14, v14, v15, v16
	v_med3_i32 v15, v32, s71, v235
	v_lshlrev_b32_e32 v13, 8, v13
	v_lshlrev_b32_e32 v12, 16, v12
	v_med3_i32 v11, v11, s71, v235
	v_cvt_i32_f32_e32 v10, v10
	v_cvt_i32_f32_e32 v7, v7
	v_mul_f32_e32 v4, v5, v4
	v_mul_f32_e32 v3, v5, v3
	v_and_b32_e32 v13, 0xff00, v13
	v_and_b32_e32 v12, 0xff0000, v12
	v_perm_b32 v11, v11, v15, s48
	v_mul_f32_e32 v6, v5, v6
	v_rndne_f32_e32 v4, v4
	v_rndne_f32_e32 v3, v3
	v_mul_f32_e32 v2, v5, v2
	v_or3_b32 v15, v11, v13, v12
	v_rndne_f32_e32 v6, v6
	v_cvt_i32_f32_e32 v11, v4
	v_cvt_i32_f32_e32 v3, v3
	v_rndne_f32_e32 v2, v2
	v_med3_i32 v9, v9, s71, v235
	v_med3_i32 v8, v8, s71, v235
	v_cvt_i32_f32_e32 v6, v6
	v_cvt_i32_f32_e32 v2, v2
	v_med3_i32 v10, v10, s71, v235
	v_lshlrev_b32_e32 v9, 8, v9
	v_lshlrev_b32_e32 v8, 16, v8
	v_med3_i32 v7, v7, s71, v235
	v_and_b32_e32 v8, 0xff0000, v8
	v_lshlrev_b32_e32 v7, 24, v7
	v_perm_b32 v4, v9, v10, s49
	v_or3_b32 v4, v4, v7, v8
	v_med3_i32 v7, v11, s71, v235
	v_med3_i32 v3, v3, s71, v235
	v_med3_i32 v6, v6, s71, v235
	v_lshlrev_b32_e32 v7, 8, v7
	v_lshlrev_b32_e32 v3, 16, v3
	v_med3_i32 v2, v2, s71, v235
	v_and_b32_e32 v7, 0xff00, v7
	v_and_b32_e32 v3, 0xff0000, v3
	v_perm_b32 v2, v2, v6, s48
	s_add_u32 s10, s10, s12
	v_or3_b32 v5, v2, v7, v3
	s_addc_u32 s11, s11, s13
	global_store_dwordx2 v[22:23], v[44:45], off offset:-1024 nt
	global_store_dwordx2 v[22:23], v[34:35], off offset:-512 nt
	global_store_dwordx2 v[22:23], v[14:15], off nt
	global_store_dwordx2 v[22:23], v[4:5], off offset:512 nt
	v_lshl_add_u64 v[18:19], v[18:19], 0, s[14:15]
	v_lshl_add_u64 v[20:21], v[20:21], 0, s[16:17]
	s_cmp_eq_u32 s1, 0
	v_lshl_add_u64 v[22:23], v[22:23], 0, s[18:19]
	s_cbranch_scc1 .LBB0_1031

.LBB0_1027:
	s_or_b64 exec, exec, s[20:21]
	s_waitcnt vmcnt(0)
	v_lshlrev_b32_e32 v48, 16, v14
	v_and_b32_e32 v47, 0xffff0000, v14
	v_max_f32_e64 v14, |v47|, |v47|
	v_max_f32_e64 v31, |v48|, |v48|
	v_lshlrev_b32_e32 v46, 16, v15
	v_and_b32_e32 v45, 0xffff0000, v15
	v_max_f32_e32 v14, v31, v14
	v_max_f32_e64 v15, |v45|, |v45|
	v_max_f32_e64 v31, |v46|, |v46|
	v_max_f32_e32 v15, v31, v15
	v_lshlrev_b32_e32 v44, 16, v16
	v_and_b32_e32 v43, 0xffff0000, v16
	v_max3_f32 v14, v14, 0, v15
	v_max_f32_e64 v15, |v43|, |v43|
	v_max_f32_e64 v16, |v44|, |v44|
	v_lshlrev_b32_e32 v41, 16, v17
	v_and_b32_e32 v40, 0xffff0000, v17
	v_max_f32_e32 v15, v16, v15
	v_max_f32_e64 v16, |v40|, |v40|
	v_max_f32_e64 v17, |v41|, |v41|
	v_max_f32_e32 v16, v17, v16
	v_lshlrev_b32_e32 v39, 16, v10
	v_and_b32_e32 v38, 0xffff0000, v10
	v_max3_f32 v14, v14, v15, v16
	v_max_f32_e64 v10, |v38|, |v38|
	v_max_f32_e64 v15, |v39|, |v39|
	v_lshlrev_b32_e32 v37, 16, v11
	v_and_b32_e32 v36, 0xffff0000, v11
	v_max_f32_e32 v10, v15, v10
	v_max_f32_e64 v11, |v36|, |v36|
	v_max_f32_e64 v15, |v37|, |v37|
	v_max_f32_e32 v11, v15, v11
	v_lshlrev_b32_e32 v35, 16, v12
	v_and_b32_e32 v34, 0xffff0000, v12
	v_max3_f32 v10, v14, v10, v11
	v_max_f32_e64 v11, |v34|, |v34|
	v_max_f32_e64 v12, |v35|, |v35|
	v_lshlrev_b32_e32 v33, 16, v13
	v_and_b32_e32 v32, 0xffff0000, v13
	v_max_f32_e32 v11, v12, v11
	v_max_f32_e64 v12, |v32|, |v32|
	v_max_f32_e64 v13, |v33|, |v33|
	v_max_f32_e32 v12, v13, v12
	v_lshlrev_b32_e32 v31, 16, v6
	v_and_b32_e32 v17, 0xffff0000, v6
	v_max3_f32 v10, v10, v11, v12
	v_max_f32_e64 v6, |v17|, |v17|
	v_max_f32_e64 v11, |v31|, |v31|
	v_lshlrev_b32_e32 v16, 16, v7
	v_and_b32_e32 v15, 0xffff0000, v7
	v_max_f32_e32 v6, v11, v6
	v_max_f32_e64 v7, |v15|, |v15|
	v_max_f32_e64 v11, |v16|, |v16|
	v_max_f32_e32 v7, v11, v7
	v_lshlrev_b32_e32 v14, 16, v8
	v_and_b32_e32 v13, 0xffff0000, v8
	v_max3_f32 v6, v10, v6, v7
	v_max_f32_e64 v7, |v13|, |v13|
	v_max_f32_e64 v8, |v14|, |v14|
	v_lshlrev_b32_e32 v12, 16, v9
	v_and_b32_e32 v11, 0xffff0000, v9
	v_max_f32_e32 v7, v8, v7
	v_max_f32_e64 v8, |v11|, |v11|
	v_max_f32_e64 v9, |v12|, |v12|
	v_max_f32_e32 v8, v9, v8
	v_lshlrev_b32_e32 v10, 16, v2
	v_and_b32_e32 v9, 0xffff0000, v2
	v_max3_f32 v6, v6, v7, v8
	v_max_f32_e64 v2, |v9|, |v9|
	v_max_f32_e64 v7, |v10|, |v10|
	v_max_f32_e32 v2, v7, v2
	v_lshlrev_b32_e32 v8, 16, v3
	v_and_b32_e32 v7, 0xffff0000, v3
	v_max_f32_e64 v3, |v7|, |v7|
	v_max_f32_e64 v50, |v8|, |v8|
	v_max_f32_e32 v3, v50, v3
	v_max3_f32 v50, v6, v2, v3
	v_lshlrev_b32_e32 v6, 16, v4
	v_and_b32_e32 v4, 0xffff0000, v4
	v_max_f32_e64 v2, |v4|, |v4|
	v_max_f32_e64 v3, |v6|, |v6|
	v_max_f32_e32 v51, v3, v2
	v_lshlrev_b32_e32 v3, 16, v5
	v_and_b32_e32 v2, 0xffff0000, v5
	v_max_f32_e64 v5, |v2|, |v2|
	v_max_f32_e64 v52, |v3|, |v3|
	v_max_f32_e32 v5, v52, v5
	v_max3_f32 v5, v50, v51, v5
	ds_bpermute_b32 v50, v25, v5
	s_waitcnt lgkmcnt(0)
	v_max_f32_e32 v50, v50, v50
	v_max_f32_e32 v5, v5, v50
	ds_bpermute_b32 v50, v25, v49
	ds_bpermute_b32 v51, v26, v5
	s_waitcnt lgkmcnt(1)
	v_add_f32_e32 v49, v49, v50
	s_waitcnt lgkmcnt(0)
	v_max_f32_e32 v50, v51, v51
	ds_bpermute_b32 v51, v26, v49
	v_max_f32_e32 v5, v5, v50
	ds_bpermute_b32 v50, v27, v5
	s_waitcnt lgkmcnt(1)
	v_add_f32_e32 v49, v49, v51
	ds_bpermute_b32 v51, v27, v49
	s_waitcnt lgkmcnt(1)
	v_max_f32_e32 v50, v50, v50
	v_max_f32_e32 v5, v5, v50
	ds_bpermute_b32 v50, v28, v5
	s_waitcnt lgkmcnt(1)
	v_add_f32_e32 v49, v49, v51
	ds_bpermute_b32 v51, v28, v49
	s_waitcnt lgkmcnt(1)
	v_max_f32_e32 v50, v50, v50
	v_max_f32_e32 v5, v5, v50
	ds_bpermute_b32 v50, v29, v5
	s_waitcnt lgkmcnt(1)
	v_add_f32_e32 v49, v49, v51
	ds_bpermute_b32 v51, v29, v49
	s_waitcnt lgkmcnt(1)
	v_max_f32_e32 v50, v50, v50
	v_max_f32_e32 v5, v5, v50
	s_waitcnt lgkmcnt(0)
	v_add_f32_e32 v49, v49, v51
	ds_bpermute_b32 v51, v30, v5
	ds_bpermute_b32 v50, v30, v49
	s_waitcnt lgkmcnt(1)
	v_max3_f32 v5, v5, v51, s73
	s_and_saveexec_b64 s[20:21], s[38:39]
	s_cbranch_execz .LBB0_1024
	s_waitcnt lgkmcnt(0)
	v_add_f32_e32 v49, v49, v50
	v_fmamk_f32 v49, v49, 0x3a000000, v1
	v_mul_f32_e32 v50, 0x4f800000, v49
	v_cmp_gt_f32_e32 vcc, s70, v49
	s_nop 1
	v_cndmask_b32_e32 v49, v49, v50, vcc
	v_sqrt_f32_e32 v50, v49
	s_nop 0
	v_add_u32_e32 v51, -1, v50
	v_fma_f32 v53, -v51, v50, v49
	v_add_u32_e32 v52, 1, v50
	v_cmp_ge_f32_e64 s[40:41], 0, v53
	s_nop 1
	v_cndmask_b32_e64 v51, v50, v51, s[40:41]
	v_fma_f32 v50, -v52, v50, v49
	v_cmp_lt_f32_e64 s[40:41], 0, v50
	s_nop 1
	v_cndmask_b32_e64 v50, v51, v52, s[40:41]
	v_mul_f32_e32 v51, 0x37800000, v50
	v_cndmask_b32_e32 v50, v50, v51, vcc
	v_cmp_class_f32_e32 vcc, v49, v226
	s_nop 1
	v_cndmask_b32_e32 v49, v50, v49, vcc
	v_div_scale_f32 v50, s[26:27], v49, v49, 1.0
	v_rcp_f32_e32 v51, v50
	s_nop 0
	v_fma_f32 v52, -v50, v51, 1.0
	v_fmac_f32_e32 v51, v52, v51
	v_div_scale_f32 v52, vcc, 1.0, v49, 1.0
	v_mul_f32_e32 v53, v52, v51
	v_fma_f32 v54, -v50, v53, v52
	v_fmac_f32_e32 v53, v54, v51
	v_fma_f32 v50, -v50, v53, v52
	v_div_fmas_f32 v50, v50, v51, v53
	v_div_fixup_f32 v49, v50, v49, 1.0
	v_mul_f32_e32 v50, 0x3c010204, v5
	v_mul_f32_e32 v49, v50, v49
	global_store_dword v115, v49, s[10:11] nt
	s_branch .LBB0_1024

.LBB0_1034:
	s_ashr_i32 s13, s25, 4
	s_lshl_b32 s14, s13, 8
	s_lshl_b32 s12, s13, 7
	s_and_b32 s15, s4, 0x780
	s_add_i32 s16, s14, 0xffffd420
	s_cmp_lt_i32 s13, 44
	s_cselect_b32 s14, s14, s16
	s_ashr_i32 s13, s12, 31
	s_lshl_b64 s[12:13], s[12:13], 2
	v_lshl_add_u64 v[2:3], v[6:7], 0, s[12:13]
	global_load_dwordx4 v[2:5], v[2:3], off
	v_add_u32_e32 v14, s15, v43
	v_lshl_add_u64 v[12:13], v[8:9], 0, s[12:13]
	v_ashrrev_i32_e32 v15, 31, v14
	s_waitcnt vmcnt(0)
	v_max_f32_e32 v2, v2, v2
	v_max_f32_e32 v2, 0xda24260, v2
	v_div_scale_f32 v3, s[16:17], v2, v2, s47
	v_rcp_f32_e32 v4, v3
	s_nop 0
	v_fma_f32 v5, -v3, v4, 1.0
	v_fmac_f32_e32 v4, v5, v4
	v_div_scale_f32 v5, vcc, s47, v2, s47
	v_mul_f32_e32 v10, v5, v4
	v_fma_f32 v11, -v3, v10, v5
	v_fmac_f32_e32 v10, v11, v4
	v_fma_f32 v3, -v3, v10, v5
	v_div_fmas_f32 v3, v3, v4, v10
	v_div_fixup_f32 v10, v3, v2, s47
	v_mad_i64_i32 v[2:3], s[12:13], v14, s18, v[12:13]
	v_lshl_add_u64 v[14:15], v[14:15], 2, s[10:11]
	global_load_dwordx4 v[2:5], v[2:3], off
	s_nop 0
	global_load_dword v14, v[14:15], off
	s_waitcnt vmcnt(0)
	v_pk_mul_f32 v[2:3], v[2:3], v[14:15] op_sel_hi:[1,0]
	v_pk_mul_f32 v[4:5], v[4:5], v[14:15] op_sel_hi:[1,0]
	v_add_u32_e32 v14, s15, v44
	v_pk_mul_f32 v[2:3], v[10:11], v[2:3] op_sel_hi:[0,1]
	v_ashrrev_i32_e32 v15, 31, v14
	v_pk_mul_f32 v[4:5], v[10:11], v[4:5] op_sel_hi:[0,1]
	ds_write2_b32 v55, v2, v3 offset1:1
	ds_write2_b32 v55, v4, v5 offset0:2 offset1:3
	v_mad_i64_i32 v[2:3], s[12:13], v14, s18, v[12:13]
	v_lshl_add_u64 v[14:15], v[14:15], 2, s[10:11]
	global_load_dwordx4 v[2:5], v[2:3], off
	s_nop 0
	global_load_dword v14, v[14:15], off
	s_waitcnt vmcnt(0)
	v_pk_mul_f32 v[2:3], v[2:3], v[14:15] op_sel_hi:[1,0]
	v_pk_mul_f32 v[4:5], v[4:5], v[14:15] op_sel_hi:[1,0]
	v_add_u32_e32 v14, s15, v45
	v_pk_mul_f32 v[2:3], v[10:11], v[2:3] op_sel_hi:[0,1]
	v_ashrrev_i32_e32 v15, 31, v14
	v_pk_mul_f32 v[4:5], v[10:11], v[4:5] op_sel_hi:[0,1]
	ds_write2_b32 v56, v2, v3 offset1:1
	ds_write2_b32 v56, v4, v5 offset0:2 offset1:3
	v_mad_i64_i32 v[2:3], s[12:13], v14, s18, v[12:13]
	v_lshl_add_u64 v[14:15], v[14:15], 2, s[10:11]
	global_load_dwordx4 v[2:5], v[2:3], off
	s_nop 0
	global_load_dword v14, v[14:15], off
	s_waitcnt vmcnt(0)
	v_pk_mul_f32 v[2:3], v[2:3], v[14:15] op_sel_hi:[1,0]
	v_pk_mul_f32 v[4:5], v[4:5], v[14:15] op_sel_hi:[1,0]
	v_add_u32_e32 v14, s15, v46
	v_pk_mul_f32 v[2:3], v[10:11], v[2:3] op_sel_hi:[0,1]
	v_ashrrev_i32_e32 v15, 31, v14
	v_pk_mul_f32 v[4:5], v[10:11], v[4:5] op_sel_hi:[0,1]
	ds_write2_b32 v57, v2, v3 offset1:1
	ds_write2_b32 v57, v4, v5 offset0:2 offset1:3
	v_mad_i64_i32 v[2:3], s[12:13], v14, s18, v[12:13]
	v_lshl_add_u64 v[14:15], v[14:15], 2, s[10:11]
	global_load_dwordx4 v[2:5], v[2:3], off
	s_nop 0
	global_load_dword v14, v[14:15], off
	s_waitcnt vmcnt(0)
	v_pk_mul_f32 v[2:3], v[2:3], v[14:15] op_sel_hi:[1,0]
	v_pk_mul_f32 v[4:5], v[4:5], v[14:15] op_sel_hi:[1,0]
	v_add_u32_e32 v14, s15, v47
	v_pk_mul_f32 v[2:3], v[10:11], v[2:3] op_sel_hi:[0,1]
	v_ashrrev_i32_e32 v15, 31, v14
	v_pk_mul_f32 v[4:5], v[10:11], v[4:5] op_sel_hi:[0,1]
	ds_write2_b32 v58, v2, v3 offset1:1
	ds_write2_b32 v58, v4, v5 offset0:2 offset1:3
	v_mad_i64_i32 v[2:3], s[12:13], v14, s18, v[12:13]
	v_lshl_add_u64 v[14:15], v[14:15], 2, s[10:11]
	global_load_dwordx4 v[2:5], v[2:3], off
	s_nop 0
	global_load_dword v14, v[14:15], off
	s_waitcnt vmcnt(0)
	v_pk_mul_f32 v[2:3], v[2:3], v[14:15] op_sel_hi:[1,0]
	v_pk_mul_f32 v[4:5], v[4:5], v[14:15] op_sel_hi:[1,0]
	v_add_u32_e32 v14, s15, v48
	v_pk_mul_f32 v[2:3], v[10:11], v[2:3] op_sel_hi:[0,1]
	v_ashrrev_i32_e32 v15, 31, v14
	v_pk_mul_f32 v[4:5], v[10:11], v[4:5] op_sel_hi:[0,1]
	ds_write2_b32 v59, v2, v3 offset1:1
	ds_write2_b32 v59, v4, v5 offset0:2 offset1:3
	v_mad_i64_i32 v[2:3], s[12:13], v14, s18, v[12:13]
	v_lshl_add_u64 v[14:15], v[14:15], 2, s[10:11]
	global_load_dwordx4 v[2:5], v[2:3], off
	s_nop 0
	global_load_dword v14, v[14:15], off
	s_waitcnt vmcnt(0)
	v_pk_mul_f32 v[2:3], v[2:3], v[14:15] op_sel_hi:[1,0]
	v_pk_mul_f32 v[4:5], v[4:5], v[14:15] op_sel_hi:[1,0]
	v_add_u32_e32 v14, s15, v49
	v_pk_mul_f32 v[2:3], v[10:11], v[2:3] op_sel_hi:[0,1]
	v_ashrrev_i32_e32 v15, 31, v14
	v_pk_mul_f32 v[4:5], v[10:11], v[4:5] op_sel_hi:[0,1]
	ds_write2_b32 v60, v2, v3 offset1:1
	ds_write2_b32 v60, v4, v5 offset0:2 offset1:3
	v_mad_i64_i32 v[2:3], s[12:13], v14, s18, v[12:13]
	v_lshl_add_u64 v[14:15], v[14:15], 2, s[10:11]
	global_load_dwordx4 v[2:5], v[2:3], off
	s_nop 0
	global_load_dword v14, v[14:15], off
	s_waitcnt vmcnt(0)
	v_pk_mul_f32 v[2:3], v[2:3], v[14:15] op_sel_hi:[1,0]
	v_pk_mul_f32 v[4:5], v[4:5], v[14:15] op_sel_hi:[1,0]
	v_add_u32_e32 v14, s15, v50
	v_pk_mul_f32 v[2:3], v[10:11], v[2:3] op_sel_hi:[0,1]
	v_ashrrev_i32_e32 v15, 31, v14
	v_pk_mul_f32 v[4:5], v[10:11], v[4:5] op_sel_hi:[0,1]
	ds_write2_b32 v61, v2, v3 offset1:1
	ds_write2_b32 v61, v4, v5 offset0:2 offset1:3
	v_mad_i64_i32 v[2:3], s[12:13], v14, s18, v[12:13]
	v_lshl_add_u64 v[12:13], v[14:15], 2, s[10:11]
	global_load_dwordx4 v[2:5], v[2:3], off
	s_add_u32 s12, s1, s15
	global_load_dword v12, v[12:13], off
	s_addc_u32 s13, s3, 0
	s_add_i32 s25, s25, s24
	s_add_i32 s4, s4, s7
	s_cmpk_gt_i32 s25, 0x57f
	s_waitcnt vmcnt(0)
	v_pk_mul_f32 v[2:3], v[2:3], v[12:13] op_sel_hi:[1,0]
	v_pk_mul_f32 v[4:5], v[4:5], v[12:13] op_sel_hi:[1,0]
	v_pk_mul_f32 v[2:3], v[10:11], v[2:3] op_sel_hi:[0,1]
	v_pk_mul_f32 v[4:5], v[10:11], v[4:5] op_sel_hi:[0,1]
	ds_write2_b32 v62, v2, v3 offset1:1
	ds_write2_b32 v62, v4, v5 offset0:2 offset1:3
	s_waitcnt lgkmcnt(0)
	s_barrier
	ds_read2_b32 v[12:13], v51 offset0:129 offset1:193
	ds_read2st64_b32 v[10:11], v51 offset1:1
	v_add_u32_e32 v4, 12, v51
	ds_read2st64_b32 v[16:17], v4 offset0:6 offset1:7
	v_add_u32_e32 v5, 28, v51
	s_waitcnt lgkmcnt(2)
	v_rndne_f32_e32 v3, v12
	s_waitcnt lgkmcnt(1)
	v_rndne_f32_e32 v2, v10
	v_cvt_i32_f32_e32 v3, v3
	v_cvt_i32_f32_e32 v2, v2
	s_waitcnt lgkmcnt(0)
	v_rndne_f32_e32 v4, v16
	v_cvt_i32_f32_e32 v4, v4
	v_med3_i32 v3, v3, s71, v235
	v_med3_i32 v2, v2, s71, v235
	v_lshlrev_b32_e32 v3, 8, v3
	v_perm_b32 v2, v3, v2, s49
	v_add_u32_e32 v3, 8, v51
	ds_read2st64_b32 v[14:15], v3 offset0:4 offset1:5
	v_med3_i32 v4, v4, s71, v235
	v_lshlrev_b32_e32 v4, 24, v4
	ds_read2st64_b32 v[24:25], v5 offset0:14 offset1:15
	v_add_u32_e32 v10, 44, v51
	s_waitcnt lgkmcnt(1)
	v_rndne_f32_e32 v3, v14
	v_cvt_i32_f32_e32 v3, v3
	ds_read2st64_b32 v[32:33], v10 offset0:22 offset1:23
	s_waitcnt lgkmcnt(1)
	v_rndne_f32_e32 v5, v24
	v_cvt_i32_f32_e32 v5, v5
	v_med3_i32 v3, v3, s71, v235
	v_lshlrev_b32_e32 v3, 16, v3
	v_and_b32_e32 v3, 0xff0000, v3
	v_or3_b32 v2, v2, v3, v4
	v_add_u32_e32 v4, 20, v51
	v_add_u32_e32 v3, 16, v51
	ds_read2st64_b32 v[20:21], v4 offset0:10 offset1:11
	ds_read2st64_b32 v[18:19], v3 offset0:8 offset1:9
	v_med3_i32 v5, v5, s71, v235
	v_lshlrev_b32_e32 v5, 24, v5
	s_waitcnt lgkmcnt(2)
	v_rndne_f32_e32 v10, v32
	s_waitcnt lgkmcnt(1)
	v_rndne_f32_e32 v4, v20
	s_waitcnt lgkmcnt(0)
	v_rndne_f32_e32 v3, v18
	v_cvt_i32_f32_e32 v4, v4
	v_cvt_i32_f32_e32 v3, v3
	v_cvt_i32_f32_e32 v10, v10
	v_add_u32_e32 v12, 60, v51
	v_med3_i32 v4, v4, s71, v235
	v_med3_i32 v3, v3, s71, v235
	v_lshlrev_b32_e32 v4, 8, v4
	v_perm_b32 v3, v4, v3, s49
	v_add_u32_e32 v4, 24, v51
	ds_read2st64_b32 v[22:23], v4 offset0:12 offset1:13
	v_med3_i32 v10, v10, s71, v235
	v_lshlrev_b32_e32 v10, 24, v10
	ds_read2st64_b32 v[40:41], v12 offset0:30 offset1:31
	s_waitcnt lgkmcnt(1)
	v_rndne_f32_e32 v4, v22
	v_cvt_i32_f32_e32 v4, v4
	s_waitcnt lgkmcnt(0)
	v_rndne_f32_e32 v12, v40
	v_cvt_i32_f32_e32 v12, v12
	v_med3_i32 v4, v4, s71, v235
	v_lshlrev_b32_e32 v4, 16, v4
	v_and_b32_e32 v4, 0xff0000, v4
	v_or3_b32 v3, v3, v4, v5
	v_add_u32_e32 v5, 36, v51
	v_add_u32_e32 v4, 32, v51
	ds_read2st64_b32 v[28:29], v5 offset0:18 offset1:19
	ds_read2st64_b32 v[26:27], v4 offset0:16 offset1:17
	v_med3_i32 v12, v12, s71, v235
	v_lshlrev_b32_e32 v12, 24, v12
	s_waitcnt lgkmcnt(1)
	v_rndne_f32_e32 v5, v28
	s_waitcnt lgkmcnt(0)
	v_rndne_f32_e32 v4, v26
	v_cvt_i32_f32_e32 v5, v5
	v_cvt_i32_f32_e32 v4, v4
	v_med3_i32 v5, v5, s71, v235
	v_med3_i32 v4, v4, s71, v235
	v_lshlrev_b32_e32 v5, 8, v5
	v_perm_b32 v4, v5, v4, s49
	v_add_u32_e32 v5, 40, v51
	ds_read2st64_b32 v[30:31], v5 offset0:20 offset1:21
	s_waitcnt lgkmcnt(0)
	v_rndne_f32_e32 v5, v30
	v_cvt_i32_f32_e32 v5, v5
	v_med3_i32 v5, v5, s71, v235
	v_lshlrev_b32_e32 v5, 16, v5
	v_and_b32_e32 v5, 0xff0000, v5
	v_or3_b32 v4, v4, v5, v10
	v_add_u32_e32 v10, 52, v51
	v_add_u32_e32 v5, 48, v51
	ds_read2st64_b32 v[36:37], v10 offset0:26 offset1:27
	ds_read2st64_b32 v[34:35], v5 offset0:24 offset1:25
	s_waitcnt lgkmcnt(1)
	v_rndne_f32_e32 v10, v36
	s_waitcnt lgkmcnt(0)
	v_rndne_f32_e32 v5, v34
	v_cvt_i32_f32_e32 v10, v10
	v_cvt_i32_f32_e32 v5, v5
	v_med3_i32 v10, v10, s71, v235
	v_med3_i32 v5, v5, s71, v235
	v_lshlrev_b32_e32 v10, 8, v10
	v_perm_b32 v5, v10, v5, s49
	v_add_u32_e32 v10, 56, v51
	ds_read2st64_b32 v[38:39], v10 offset0:28 offset1:29
	s_waitcnt lgkmcnt(0)
	v_rndne_f32_e32 v10, v38
	v_cvt_i32_f32_e32 v10, v10
	v_med3_i32 v10, v10, s71, v235
	v_lshlrev_b32_e32 v10, 16, v10
	v_and_b32_e32 v10, 0xff0000, v10
	v_or3_b32 v5, v5, v10, v12
	v_or_b32_e32 v10, s14, v53
	v_add_u32_e32 v64, v10, v52
	v_ashrrev_i32_e32 v65, 31, v64
	v_lshlrev_b64 v[64:65], 11, v[64:65]
	v_lshl_add_u64 v[64:65], s[12:13], 0, v[64:65]
	v_lshl_add_u64 v[64:65], v[64:65], 0, v[114:115]
	global_store_dwordx4 v[64:65], v[2:5], off nt
	v_rndne_f32_e32 v12, v41
	v_cvt_i32_f32_e32 v12, v12
	v_rndne_f32_e32 v3, v13
	v_rndne_f32_e32 v2, v11
	v_cvt_i32_f32_e32 v3, v3
	v_cvt_i32_f32_e32 v2, v2
	v_rndne_f32_e32 v4, v17
	v_cvt_i32_f32_e32 v4, v4
	v_med3_i32 v3, v3, s71, v235
	v_med3_i32 v2, v2, s71, v235
	v_lshlrev_b32_e32 v3, 8, v3
	v_perm_b32 v2, v3, v2, s49
	v_rndne_f32_e32 v3, v15
	v_cvt_i32_f32_e32 v3, v3
	v_med3_i32 v4, v4, s71, v235
	v_lshlrev_b32_e32 v4, 24, v4
	v_rndne_f32_e32 v5, v25
	v_med3_i32 v3, v3, s71, v235
	v_lshlrev_b32_e32 v3, 16, v3
	v_and_b32_e32 v3, 0xff0000, v3
	v_or3_b32 v2, v2, v3, v4
	v_rndne_f32_e32 v4, v21
	v_rndne_f32_e32 v3, v19
	v_cvt_i32_f32_e32 v4, v4
	v_cvt_i32_f32_e32 v3, v3
	v_cvt_i32_f32_e32 v5, v5
	v_rndne_f32_e32 v11, v33
	v_med3_i32 v4, v4, s71, v235
	v_med3_i32 v3, v3, s71, v235
	v_lshlrev_b32_e32 v4, 8, v4
	v_perm_b32 v3, v4, v3, s49
	v_rndne_f32_e32 v4, v23
	v_cvt_i32_f32_e32 v4, v4
	v_med3_i32 v5, v5, s71, v235
	v_lshlrev_b32_e32 v5, 24, v5
	v_cvt_i32_f32_e32 v11, v11
	v_med3_i32 v4, v4, s71, v235
	v_lshlrev_b32_e32 v4, 16, v4
	v_and_b32_e32 v4, 0xff0000, v4
	v_or3_b32 v3, v3, v4, v5
	v_rndne_f32_e32 v5, v29
	v_rndne_f32_e32 v4, v27
	v_cvt_i32_f32_e32 v5, v5
	v_cvt_i32_f32_e32 v4, v4
	v_med3_i32 v11, v11, s71, v235
	v_lshlrev_b32_e32 v11, 24, v11
	v_med3_i32 v5, v5, s71, v235
	v_med3_i32 v4, v4, s71, v235
	v_lshlrev_b32_e32 v5, 8, v5
	v_perm_b32 v4, v5, v4, s49
	v_rndne_f32_e32 v5, v31
	v_cvt_i32_f32_e32 v5, v5
	v_med3_i32 v12, v12, s71, v235
	v_lshlrev_b32_e32 v12, 24, v12
	v_add_u32_e32 v10, v10, v54
	v_med3_i32 v5, v5, s71, v235
	v_lshlrev_b32_e32 v5, 16, v5
	v_and_b32_e32 v5, 0xff0000, v5
	v_or3_b32 v4, v4, v5, v11
	v_rndne_f32_e32 v11, v37
	v_rndne_f32_e32 v5, v35
	v_cvt_i32_f32_e32 v11, v11
	v_cvt_i32_f32_e32 v5, v5
	v_med3_i32 v11, v11, s71, v235
	v_med3_i32 v5, v5, s71, v235
	v_lshlrev_b32_e32 v11, 8, v11
	v_perm_b32 v5, v11, v5, s49
	v_rndne_f32_e32 v11, v39
	v_cvt_i32_f32_e32 v11, v11
	v_med3_i32 v11, v11, s71, v235
	v_lshlrev_b32_e32 v11, 16, v11
	v_and_b32_e32 v11, 0xff0000, v11
	v_or3_b32 v5, v5, v11, v12
	v_ashrrev_i32_e32 v11, 31, v10
	v_lshlrev_b64 v[10:11], 11, v[10:11]
	v_lshl_add_u64 v[10:11], s[12:13], 0, v[10:11]
	v_lshl_add_u64 v[10:11], v[10:11], 0, v[114:115]
	global_store_dwordx4 v[10:11], v[2:5], off nt
	s_barrier
	s_cbranch_scc0 .LBB0_1034

.LBB0_1037:
	s_or_b64 exec, exec, s[6:7]
	v_div_scale_f32 v47, s[6:7], v5, v5, s47
	s_waitcnt lgkmcnt(0)
	v_rcp_f32_e32 v48, v47
	v_div_scale_f32 v49, vcc, s47, v5, s47
	s_add_i32 s22, s22, -1
	v_fma_f32 v50, -v47, v48, 1.0
	v_fmac_f32_e32 v48, v50, v48
	v_mul_f32_e32 v50, v49, v48
	v_fma_f32 v51, -v47, v50, v49
	v_fmac_f32_e32 v50, v51, v48
	v_fma_f32 v47, -v47, v50, v49
	v_div_fmas_f32 v47, v47, v48, v50
	v_div_fixup_f32 v5, v47, v5, s47
	v_mul_f32_e32 v45, v5, v45
	v_mul_f32_e32 v44, v5, v44
	v_mul_f32_e32 v46, v5, v46
	v_rndne_f32_e32 v45, v45
	v_rndne_f32_e32 v44, v44
	v_mul_f32_e32 v43, v5, v43
	v_rndne_f32_e32 v46, v46
	v_cvt_i32_f32_e32 v45, v45
	v_cvt_i32_f32_e32 v44, v44
	v_rndne_f32_e32 v43, v43
	v_mul_f32_e32 v41, v5, v41
	v_mul_f32_e32 v40, v5, v40
	v_cvt_i32_f32_e32 v46, v46
	v_cvt_i32_f32_e32 v43, v43
	v_mul_f32_e32 v42, v5, v42
	v_rndne_f32_e32 v41, v41
	v_rndne_f32_e32 v40, v40
	v_mul_f32_e32 v39, v5, v39
	v_rndne_f32_e32 v42, v42
	v_cvt_i32_f32_e32 v41, v41
	v_cvt_i32_f32_e32 v40, v40
	v_rndne_f32_e32 v39, v39
	v_cvt_i32_f32_e32 v47, v42
	v_cvt_i32_f32_e32 v39, v39
	v_med3_i32 v45, v45, s71, v235
	v_med3_i32 v44, v44, s71, v235
	v_mul_f32_e32 v37, v5, v37
	v_mul_f32_e32 v36, v5, v36
	v_med3_i32 v46, v46, s71, v235
	v_lshlrev_b32_e32 v45, 8, v45
	v_lshlrev_b32_e32 v44, 16, v44
	v_med3_i32 v43, v43, s71, v235
	v_mul_f32_e32 v38, v5, v38
	v_rndne_f32_e32 v37, v37
	v_rndne_f32_e32 v36, v36
	v_mul_f32_e32 v35, v5, v35
	v_and_b32_e32 v44, 0xff0000, v44
	v_lshlrev_b32_e32 v43, 24, v43
	v_perm_b32 v42, v45, v46, s49
	v_med3_i32 v41, v41, s71, v235
	v_med3_i32 v40, v40, s71, v235
	v_rndne_f32_e32 v38, v38
	v_cvt_i32_f32_e32 v37, v37
	v_cvt_i32_f32_e32 v36, v36
	v_rndne_f32_e32 v35, v35
	v_mul_f32_e32 v33, v5, v33
	v_mul_f32_e32 v32, v5, v32
	v_or3_b32 v42, v42, v43, v44
	v_med3_i32 v43, v47, s71, v235
	v_lshlrev_b32_e32 v41, 8, v41
	v_lshlrev_b32_e32 v40, 16, v40
	v_med3_i32 v39, v39, s71, v235
	v_cvt_i32_f32_e32 v38, v38
	v_cvt_i32_f32_e32 v35, v35
	v_mul_f32_e32 v34, v5, v34
	v_rndne_f32_e32 v33, v33
	v_rndne_f32_e32 v32, v32
	v_mul_f32_e32 v31, v5, v31
	v_and_b32_e32 v41, 0xff00, v41
	v_and_b32_e32 v40, 0xff0000, v40
	v_perm_b32 v39, v39, v43, s48
	v_rndne_f32_e32 v34, v34
	v_cvt_i32_f32_e32 v33, v33
	v_cvt_i32_f32_e32 v32, v32
	v_rndne_f32_e32 v31, v31
	v_or3_b32 v43, v39, v41, v40
	v_cvt_i32_f32_e32 v39, v34
	v_cvt_i32_f32_e32 v31, v31
	v_med3_i32 v37, v37, s71, v235
	v_med3_i32 v36, v36, s71, v235
	v_mul_f32_e32 v17, v5, v17
	v_mul_f32_e32 v16, v5, v16
	v_med3_i32 v38, v38, s71, v235
	v_lshlrev_b32_e32 v37, 8, v37
	v_lshlrev_b32_e32 v36, 16, v36
	v_med3_i32 v35, v35, s71, v235
	v_mul_f32_e32 v30, v5, v30
	v_rndne_f32_e32 v17, v17
	v_rndne_f32_e32 v16, v16
	v_mul_f32_e32 v15, v5, v15
	v_and_b32_e32 v36, 0xff0000, v36
	v_lshlrev_b32_e32 v35, 24, v35
	v_perm_b32 v34, v37, v38, s49
	v_med3_i32 v33, v33, s71, v235
	v_med3_i32 v32, v32, s71, v235
	v_rndne_f32_e32 v30, v30
	v_cvt_i32_f32_e32 v17, v17
	v_cvt_i32_f32_e32 v16, v16
	v_rndne_f32_e32 v15, v15
	v_mul_f32_e32 v13, v5, v13
	v_mul_f32_e32 v12, v5, v12
	v_or3_b32 v34, v34, v35, v36
	v_med3_i32 v35, v39, s71, v235
	v_lshlrev_b32_e32 v33, 8, v33
	v_lshlrev_b32_e32 v32, 16, v32
	v_med3_i32 v31, v31, s71, v235
	v_cvt_i32_f32_e32 v30, v30
	v_cvt_i32_f32_e32 v15, v15
	v_mul_f32_e32 v14, v5, v14
	v_rndne_f32_e32 v13, v13
	v_rndne_f32_e32 v12, v12
	v_mul_f32_e32 v11, v5, v11
	v_and_b32_e32 v33, 0xff00, v33
	v_and_b32_e32 v32, 0xff0000, v32
	v_perm_b32 v31, v31, v35, s48
	v_rndne_f32_e32 v14, v14
	v_cvt_i32_f32_e32 v13, v13
	v_cvt_i32_f32_e32 v12, v12
	v_rndne_f32_e32 v11, v11
	v_or3_b32 v35, v31, v33, v32
	v_cvt_i32_f32_e32 v31, v14
	v_cvt_i32_f32_e32 v11, v11
	v_med3_i32 v17, v17, s71, v235
	v_med3_i32 v16, v16, s71, v235
	v_mul_f32_e32 v9, v5, v9
	v_mul_f32_e32 v8, v5, v8
	v_med3_i32 v30, v30, s71, v235
	v_lshlrev_b32_e32 v17, 8, v17
	v_lshlrev_b32_e32 v16, 16, v16
	v_med3_i32 v15, v15, s71, v235
	v_mul_f32_e32 v10, v5, v10
	v_rndne_f32_e32 v9, v9
	v_rndne_f32_e32 v8, v8
	v_mul_f32_e32 v7, v5, v7
	v_and_b32_e32 v16, 0xff0000, v16
	v_lshlrev_b32_e32 v15, 24, v15
	v_perm_b32 v14, v17, v30, s49
	v_med3_i32 v13, v13, s71, v235
	v_med3_i32 v12, v12, s71, v235
	v_rndne_f32_e32 v10, v10
	v_cvt_i32_f32_e32 v9, v9
	v_cvt_i32_f32_e32 v8, v8
	v_rndne_f32_e32 v7, v7
	v_or3_b32 v14, v14, v15, v16
	v_med3_i32 v15, v31, s71, v235
	v_lshlrev_b32_e32 v13, 8, v13
	v_lshlrev_b32_e32 v12, 16, v12
	v_med3_i32 v11, v11, s71, v235
	v_cvt_i32_f32_e32 v10, v10
	v_cvt_i32_f32_e32 v7, v7
	v_mul_f32_e32 v4, v5, v4
	v_mul_f32_e32 v3, v5, v3
	v_and_b32_e32 v13, 0xff00, v13
	v_and_b32_e32 v12, 0xff0000, v12
	v_perm_b32 v11, v11, v15, s48
	v_mul_f32_e32 v6, v5, v6
	v_rndne_f32_e32 v4, v4
	v_rndne_f32_e32 v3, v3
	v_mul_f32_e32 v2, v5, v2
	v_or3_b32 v15, v11, v13, v12
	v_rndne_f32_e32 v6, v6
	v_cvt_i32_f32_e32 v11, v4
	v_cvt_i32_f32_e32 v3, v3
	v_rndne_f32_e32 v2, v2
	v_med3_i32 v9, v9, s71, v235
	v_med3_i32 v8, v8, s71, v235
	v_cvt_i32_f32_e32 v6, v6
	v_cvt_i32_f32_e32 v2, v2
	v_med3_i32 v10, v10, s71, v235
	v_lshlrev_b32_e32 v9, 8, v9
	v_lshlrev_b32_e32 v8, 16, v8
	v_med3_i32 v7, v7, s71, v235
	v_and_b32_e32 v8, 0xff0000, v8
	v_lshlrev_b32_e32 v7, 24, v7
	v_perm_b32 v4, v9, v10, s49
	v_or3_b32 v4, v4, v7, v8
	v_med3_i32 v7, v11, s71, v235
	v_med3_i32 v3, v3, s71, v235
	v_med3_i32 v6, v6, s71, v235
	v_lshlrev_b32_e32 v7, 8, v7
	v_lshlrev_b32_e32 v3, 16, v3
	v_med3_i32 v2, v2, s71, v235
	v_and_b32_e32 v7, 0xff00, v7
	v_and_b32_e32 v3, 0xff0000, v3
	v_perm_b32 v2, v2, v6, s48
	s_add_u32 s8, s8, s10
	v_or3_b32 v5, v2, v7, v3
	s_addc_u32 s9, s9, s11
	global_store_dwordx2 v[22:23], v[42:43], off offset:-1024 nt
	global_store_dwordx2 v[22:23], v[34:35], off offset:-512 nt
	global_store_dwordx2 v[22:23], v[14:15], off nt
	global_store_dwordx2 v[22:23], v[4:5], off offset:512 nt
	v_lshl_add_u64 v[18:19], v[18:19], 0, s[12:13]
	v_lshl_add_u64 v[20:21], v[20:21], 0, s[14:15]
	s_cmp_lg_u32 s22, 0
	v_lshl_add_u64 v[22:23], v[22:23], 0, s[0:1]
	s_cbranch_scc0 .LBB0_1042

.LBB0_1040:
	s_or_b64 exec, exec, s[6:7]
	s_waitcnt vmcnt(0)
	v_lshlrev_b32_e32 v46, 16, v14
	v_and_b32_e32 v45, 0xffff0000, v14
	v_max_f32_e64 v14, |v45|, |v45|
	v_max_f32_e64 v30, |v46|, |v46|
	v_lshlrev_b32_e32 v44, 16, v15
	v_and_b32_e32 v43, 0xffff0000, v15
	v_max_f32_e32 v14, v30, v14
	v_max_f32_e64 v15, |v43|, |v43|
	v_max_f32_e64 v30, |v44|, |v44|
	v_max_f32_e32 v15, v30, v15
	v_lshlrev_b32_e32 v42, 16, v16
	v_and_b32_e32 v41, 0xffff0000, v16
	v_max3_f32 v14, v14, 0, v15
	v_max_f32_e64 v15, |v41|, |v41|
	v_max_f32_e64 v16, |v42|, |v42|
	v_lshlrev_b32_e32 v40, 16, v17
	v_and_b32_e32 v39, 0xffff0000, v17
	v_max_f32_e32 v15, v16, v15
	v_max_f32_e64 v16, |v39|, |v39|
	v_max_f32_e64 v17, |v40|, |v40|
	v_max_f32_e32 v16, v17, v16
	v_lshlrev_b32_e32 v38, 16, v10
	v_and_b32_e32 v37, 0xffff0000, v10
	v_max3_f32 v14, v14, v15, v16
	v_max_f32_e64 v10, |v37|, |v37|
	v_max_f32_e64 v15, |v38|, |v38|
	v_lshlrev_b32_e32 v36, 16, v11
	v_and_b32_e32 v35, 0xffff0000, v11
	v_max_f32_e32 v10, v15, v10
	v_max_f32_e64 v11, |v35|, |v35|
	v_max_f32_e64 v15, |v36|, |v36|
	v_max_f32_e32 v11, v15, v11
	v_lshlrev_b32_e32 v34, 16, v12
	v_and_b32_e32 v33, 0xffff0000, v12
	v_max3_f32 v10, v14, v10, v11
	v_max_f32_e64 v11, |v33|, |v33|
	v_max_f32_e64 v12, |v34|, |v34|
	v_lshlrev_b32_e32 v32, 16, v13
	v_and_b32_e32 v31, 0xffff0000, v13
	v_max_f32_e32 v11, v12, v11
	v_max_f32_e64 v12, |v31|, |v31|
	v_max_f32_e64 v13, |v32|, |v32|
	v_max_f32_e32 v12, v13, v12
	v_lshlrev_b32_e32 v30, 16, v6
	v_and_b32_e32 v17, 0xffff0000, v6
	v_max3_f32 v10, v10, v11, v12
	v_max_f32_e64 v6, |v17|, |v17|
	v_max_f32_e64 v11, |v30|, |v30|
	v_lshlrev_b32_e32 v16, 16, v7
	v_and_b32_e32 v15, 0xffff0000, v7
	v_max_f32_e32 v6, v11, v6
	v_max_f32_e64 v7, |v15|, |v15|
	v_max_f32_e64 v11, |v16|, |v16|
	v_max_f32_e32 v7, v11, v7
	v_lshlrev_b32_e32 v14, 16, v8
	v_and_b32_e32 v13, 0xffff0000, v8
	v_max3_f32 v6, v10, v6, v7
	v_max_f32_e64 v7, |v13|, |v13|
	v_max_f32_e64 v8, |v14|, |v14|
	v_lshlrev_b32_e32 v12, 16, v9
	v_and_b32_e32 v11, 0xffff0000, v9
	v_max_f32_e32 v7, v8, v7
	v_max_f32_e64 v8, |v11|, |v11|
	v_max_f32_e64 v9, |v12|, |v12|
	v_max_f32_e32 v8, v9, v8
	v_lshlrev_b32_e32 v10, 16, v2
	v_and_b32_e32 v9, 0xffff0000, v2
	v_max3_f32 v6, v6, v7, v8
	v_max_f32_e64 v2, |v9|, |v9|
	v_max_f32_e64 v7, |v10|, |v10|
	v_max_f32_e32 v2, v7, v2
	v_lshlrev_b32_e32 v8, 16, v3
	v_and_b32_e32 v7, 0xffff0000, v3
	v_max_f32_e64 v3, |v7|, |v7|
	v_max_f32_e64 v48, |v8|, |v8|
	v_max_f32_e32 v3, v48, v3
	v_max3_f32 v48, v6, v2, v3
	v_lshlrev_b32_e32 v6, 16, v4
	v_and_b32_e32 v4, 0xffff0000, v4
	v_max_f32_e64 v2, |v4|, |v4|
	v_max_f32_e64 v3, |v6|, |v6|
	v_max_f32_e32 v49, v3, v2
	v_lshlrev_b32_e32 v3, 16, v5
	v_and_b32_e32 v2, 0xffff0000, v5
	v_max_f32_e64 v5, |v2|, |v2|
	v_max_f32_e64 v50, |v3|, |v3|
	v_max_f32_e32 v5, v50, v5
	v_max3_f32 v5, v48, v49, v5
	ds_bpermute_b32 v48, v24, v5
	s_waitcnt lgkmcnt(0)
	v_max_f32_e32 v48, v48, v48
	v_max_f32_e32 v5, v5, v48
	ds_bpermute_b32 v48, v24, v47
	ds_bpermute_b32 v49, v25, v5
	s_waitcnt lgkmcnt(1)
	v_add_f32_e32 v47, v47, v48
	s_waitcnt lgkmcnt(0)
	v_max_f32_e32 v48, v49, v49
	ds_bpermute_b32 v49, v25, v47
	v_max_f32_e32 v5, v5, v48
	ds_bpermute_b32 v48, v26, v5
	s_waitcnt lgkmcnt(1)
	v_add_f32_e32 v47, v47, v49
	ds_bpermute_b32 v49, v26, v47
	s_waitcnt lgkmcnt(1)
	v_max_f32_e32 v48, v48, v48
	v_max_f32_e32 v5, v5, v48
	ds_bpermute_b32 v48, v27, v5
	s_waitcnt lgkmcnt(1)
	v_add_f32_e32 v47, v47, v49
	ds_bpermute_b32 v49, v27, v47
	s_waitcnt lgkmcnt(1)
	v_max_f32_e32 v48, v48, v48
	v_max_f32_e32 v5, v5, v48
	ds_bpermute_b32 v48, v28, v5
	s_waitcnt lgkmcnt(1)
	v_add_f32_e32 v47, v47, v49
	ds_bpermute_b32 v49, v28, v47
	s_waitcnt lgkmcnt(1)
	v_max_f32_e32 v48, v48, v48
	v_max_f32_e32 v5, v5, v48
	s_waitcnt lgkmcnt(0)
	v_add_f32_e32 v47, v47, v49
	ds_bpermute_b32 v49, v29, v5
	ds_bpermute_b32 v48, v29, v47
	s_waitcnt lgkmcnt(1)
	v_max3_f32 v5, v5, v49, s73
	s_and_saveexec_b64 s[6:7], s[38:39]
	s_cbranch_execz .LBB0_1037
	s_waitcnt lgkmcnt(0)
	v_add_f32_e32 v47, v47, v48
	v_fmamk_f32 v47, v47, 0x3a000000, v1
	v_mul_f32_e32 v48, 0x4f800000, v47
	v_cmp_gt_f32_e32 vcc, s70, v47
	s_nop 1
	v_cndmask_b32_e32 v47, v47, v48, vcc
	v_sqrt_f32_e32 v48, v47
	s_nop 0
	v_add_u32_e32 v49, -1, v48
	v_fma_f32 v51, -v49, v48, v47
	v_add_u32_e32 v50, 1, v48
	v_cmp_ge_f32_e64 s[40:41], 0, v51
	s_nop 1
	v_cndmask_b32_e64 v49, v48, v49, s[40:41]
	v_fma_f32 v48, -v50, v48, v47
	v_cmp_lt_f32_e64 s[40:41], 0, v48
	s_nop 1
	v_cndmask_b32_e64 v48, v49, v50, s[40:41]
	v_mul_f32_e32 v49, 0x37800000, v48
	v_cndmask_b32_e32 v48, v48, v49, vcc
	v_cmp_class_f32_e32 vcc, v47, v226
	s_nop 1
	v_cndmask_b32_e32 v47, v48, v47, vcc
	v_div_scale_f32 v48, s[16:17], v47, v47, 1.0
	v_rcp_f32_e32 v49, v48
	s_nop 0
	v_fma_f32 v50, -v48, v49, 1.0
	v_fmac_f32_e32 v49, v50, v49
	v_div_scale_f32 v50, vcc, 1.0, v47, 1.0
	v_mul_f32_e32 v51, v50, v49
	v_fma_f32 v52, -v48, v51, v50
	v_fmac_f32_e32 v51, v52, v49
	v_fma_f32 v48, -v48, v51, v50
	v_div_fmas_f32 v48, v48, v49, v51
	v_div_fixup_f32 v47, v48, v47, 1.0
	v_mul_f32_e32 v48, 0x3c010204, v5
	v_mul_f32_e32 v47, v48, v47
	global_store_dword v115, v47, s[8:9] nt
	s_branch .LBB0_1037

.LBB0_1195:
	s_or_b64 exec, exec, s[16:17]
	s_waitcnt vmcnt(0)
	v_mul_f32_e32 v11, 0xbfb8aa3b, v7
	v_mul_f32_e32 v12, 0xbfb8aa3b, v8
	v_mul_f32_e32 v10, 0xbfb8aa3b, v6
	v_exp_f32_e32 v11, v11
	v_exp_f32_e32 v13, v12
	v_mul_f32_e32 v12, 0xbfb8aa3b, v9
	v_exp_f32_e32 v10, v10
	v_exp_f32_e32 v18, v12
	v_add_f32_e32 v11, 1.0, v11
	v_rcp_f32_e32 v12, v11
	v_add_f32_e32 v10, 1.0, v10
	v_add_f32_e32 v11, 1.0, v13
	v_add_f32_e32 v13, 1.0, v18
	v_rcp_f32_e32 v10, v10
	v_rcp_f32_e32 v11, v11
	v_rcp_f32_e32 v13, v13
	v_mov_b32_e32 v18, v6
	v_mov_b32_e32 v19, v8
	v_mov_b32_e32 v8, v7
	v_pk_mul_f32 v[10:11], v[18:19], v[10:11]
	v_mov_b32_e32 v19, v4
	v_pk_mul_f32 v[6:7], v[8:9], v[12:13]
	v_mov_b32_e32 v4, v3
	v_mov_b32_e32 v18, v2
	v_pk_mul_f32 v[2:3], v[4:5], v[6:7]
	v_pk_mul_f32 v[10:11], v[18:19], v[10:11]
	v_and_b32_sdwa v7, v2, v228 dst_sel:DWORD dst_unused:UNUSED_PAD src0_sel:WORD_1 src1_sel:DWORD
	v_and_b32_sdwa v5, v10, v228 dst_sel:DWORD dst_unused:UNUSED_PAD src0_sel:WORD_1 src1_sel:DWORD
	v_and_b32_sdwa v6, v3, v228 dst_sel:DWORD dst_unused:UNUSED_PAD src0_sel:WORD_1 src1_sel:DWORD
	v_add3_u32 v2, v2, v7, s67
	v_and_b32_sdwa v4, v11, v228 dst_sel:DWORD dst_unused:UNUSED_PAD src0_sel:WORD_1 src1_sel:DWORD
	v_add3_u32 v5, v10, v5, s67
	v_add3_u32 v3, v3, v6, s67
	v_and_b32_e32 v2, 0xffff0000, v2
	v_add3_u32 v4, v11, v4, s67
	v_and_b32_e32 v3, 0xffff0000, v3
	v_or_b32_sdwa v2, v2, v5 dst_sel:DWORD dst_unused:UNUSED_PAD src0_sel:DWORD src1_sel:WORD_1
	v_mov_b32_e32 v5, 0xff
	v_or_b32_sdwa v3, v3, v4 dst_sel:DWORD dst_unused:UNUSED_PAD src0_sel:DWORD src1_sel:WORD_1
	v_lshlrev_b32_e32 v4, 7, v16
	v_cndmask_b32_e64 v6, v5, 0, s[36:37]
	s_mov_b32 s16, 0x1ff00
	v_and_or_b32 v4, v4, s16, v6
	v_sub_u32_e32 v17, v14, v17
	v_lshrrev_b32_e32 v4, 1, v4
	v_mul_u32_u24_e32 v4, 0xb0, v4
	v_lshrrev_b32_e32 v5, 3, v17
	v_add_lshl_u32 v4, v4, v5, 7
	v_mov_b32_e32 v5, v115
	v_lshlrev_b32_e32 v6, 6, v6
	v_lshl_add_u64 v[4:5], s[8:9], 0, v[4:5]
	v_and_b32_e32 v6, 64, v6
	v_mov_b32_e32 v7, v115
	v_lshl_add_u64 v[4:5], v[4:5], 0, v[6:7]
	v_and_b32_e32 v6, 28, v114
	v_add_u32_e32 v14, s3, v14
	s_mov_b32 s16, 0x83fff
	v_lshlrev_b32_e32 v114, 1, v6
	v_cmp_lt_u32_e32 vcc, s16, v14
	v_lshl_add_u64 v[4:5], v[4:5], 0, v[114:115]
	s_or_b64 s[14:15], vcc, s[14:15]
	v_add_u32_e32 v15, s4, v15
	global_store_dwordx2 v[4:5], v[2:3], off nt
	s_andn2_b64 exec, exec, s[14:15]
	s_cbranch_execz .LBB0_1200
